# GLA chunk loops: loop-top vmcnt waits counted so they cover only the staged loads, not the previous chunk's o-store acks
# baseline (speedup 1.0000x reference)
.LBB0_326:
	s_or_b64 exec, exec, s[0:1]
	v_readlane_b32 s8, v254, 21
	v_readlane_b32 s13, v254, 26
	v_readlane_b32 s15, v254, 28
	v_readlane_b32 s12, v254, 25
	v_readlane_b32 s14, v254, 27
	v_mov_b32_e32 v30, s15
	v_mov_b32_e32 v31, s13
	v_cndmask_b32_e64 v31, v30, v31, s[2:3]
	v_mov_b32_e32 v30, s14
	v_mov_b32_e32 v36, s12
	v_lshlrev_b32_e32 v76, 4, v28
	v_cndmask_b32_e64 v30, v30, v36, s[2:3]
	v_mul_lo_u32 v36, v32, s92
	v_or_b32_e32 v37, v76, v91
	v_add_u32_e32 v36, 0, v36
	s_movk_i32 s0, 0xff72
	v_lshlrev_b32_e32 v73, 3, v25
	v_mad_u64_u32 v[78:79], s[0:1], v32, s0, v[36:37]
	v_lshlrev_b32_e32 v28, 1, v28
	v_lshl_add_u32 v92, v73, 1, v36
	v_mul_lo_u32 v36, v37, s92
	v_and_b32_e32 v37, 2, v28
	v_lshlrev_b32_e32 v28, 1, v29
	v_lshlrev_b32_e32 v29, 1, v91
	v_readlane_b32 s1, v255, 34
	v_ashrrev_i32_e32 v41, 7, v24
	v_readlane_b32 s6, v255, 35
	v_lshlrev_b32_e32 v27, 7, v86
	v_add3_u32 v39, s1, v28, v29
	v_lshl_add_u32 v28, v41, 12, s6
	v_lshlrev_b32_e32 v29, 8, v91
	v_readlane_b32 s0, v255, 33
	v_add3_u32 v42, v28, v29, v34
	v_lshlrev_b32_e32 v28, 8, v32
	v_lshlrev_b32_e32 v44, 2, v73
	v_lshlrev_b32_e32 v80, 1, v27
	v_mov_b32_e32 v81, v3
	v_add3_u32 v79, s0, v36, v72
	s_add_i32 s0, 0, 0x1e400
	v_add3_u32 v94, s6, v28, v44
	v_lshl_add_u64 v[28:29], v[30:31], 0, v[80:81]
	v_ashrrev_i32_e32 v77, 31, v76
	v_add_u32_e32 v38, s0, v34
	v_readlane_b32 s0, v255, 31
	v_lshlrev_b32_e32 v24, 4, v41
	v_lshl_add_u64 v[28:29], v[76:77], 1, v[28:29]
	v_mov_b32_e32 v27, v3
	v_mul_u32_u24_e32 v97, 0x480, v25
	v_add_u32_e32 v40, s0, v34
	v_add_u32_e32 v93, s1, v34
	v_cmp_eq_u32_e32 vcc, 3, v41
	v_cmp_eq_u32_e64 s[0:1], 15, v91
	v_lshl_add_u64 v[82:83], v[28:29], 0, v[26:27]
	v_lshlrev_b32_e32 v25, 1, v97
	v_lshlrev_b32_e32 v26, 1, v32
	v_or_b32_e32 v52, v24, v91
	s_and_b64 s[76:77], vcc, s[0:1]
	v_add_u32_e32 v98, v78, v25
	v_add3_u32 v99, 0, v25, v26
	v_or_b32_e32 v25, 2, v72
	v_mul_lo_u32 v24, v52, s92
	v_cmp_gt_i32_e32 vcc, v72, v52
	v_add3_u32 v100, 0, v24, v72
	v_or_b32_e32 v27, 3, v72
	v_cndmask_b32_e64 v24, v160, 0, vcc
	v_cmp_lt_i32_e32 vcc, v52, v25
	v_or_b32_e32 v26, 4, v72
	v_or_b32_e32 v30, 5, v72
	v_cndmask_b32_e64 v25, v160, 0, vcc
	v_cmp_lt_i32_e32 vcc, v72, v52
	v_or_b32_e32 v31, 7, v72
	v_add_u32_e32 v55, 38, v72
	v_cndmask_b32_e32 v28, 0, v160, vcc
	v_cmp_gt_i32_e32 vcc, v27, v52
	v_or_b32_e32 v27, 6, v72
	v_pack_b32_f16 v24, v24, v28
	v_cndmask_b32_e64 v29, v160, 0, vcc
	v_cmp_gt_i32_e32 vcc, v26, v52
	v_or_b32_e32 v28, 32, v72
	v_pack_b32_f16 v25, v25, v29
	v_cndmask_b32_e64 v26, v160, 0, vcc
	v_cmp_gt_i32_e32 vcc, v30, v52
	v_add_u32_e32 v29, 33, v72
	v_or_b32_e32 v48, 1, v37
	v_cndmask_b32_e64 v30, v160, 0, vcc
	v_cmp_gt_i32_e32 vcc, v27, v52
	v_pack_b32_f16 v26, v26, v30
	v_add_u32_e32 v30, 34, v72
	v_cndmask_b32_e64 v27, v160, 0, vcc
	v_cmp_gt_i32_e32 vcc, v31, v52
	v_lshlrev_b32_e32 v35, 2, v90
	v_readlane_b32 s9, v254, 22
	v_cndmask_b32_e64 v31, v160, 0, vcc
	v_cmp_gt_i32_e32 vcc, v28, v52
	v_pack_b32_f16 v27, v27, v31
	v_add_u32_e32 v31, 36, v72
	v_cndmask_b32_e64 v28, v160, 0, vcc
	v_cmp_gt_i32_e32 vcc, v29, v52
	v_readlane_b32 s0, v255, 37
	v_lshlrev_b32_e32 v45, 4, v37
	v_cndmask_b32_e64 v53, v160, 0, vcc
	v_cmp_gt_i32_e32 vcc, v30, v52
	v_add_u32_e32 v30, 35, v72
	v_lshlrev_b32_e32 v49, 4, v48
	v_cndmask_b32_e64 v29, v160, 0, vcc
	v_cmp_gt_i32_e32 vcc, v30, v52
	v_or_b32_e32 v46, v45, v91
	v_or_b32_e32 v50, v49, v91
	v_cndmask_b32_e64 v54, v160, 0, vcc
	v_cmp_gt_i32_e32 vcc, v31, v52
	v_add_u32_e32 v31, 37, v72
	v_pack_b32_f16 v28, v28, v53
	v_cndmask_b32_e64 v30, v160, 0, vcc
	v_cmp_gt_i32_e32 vcc, v31, v52
	v_add_u32_e32 v101, s0, v44
	v_or_b32_e32 v44, 1, v73
	v_cndmask_b32_e64 v56, v160, 0, vcc
	v_cmp_gt_i32_e32 vcc, v55, v52
	v_add_u32_e32 v55, 39, v72
	v_cmp_le_i32_e64 s[6:7], v37, v41
	v_cndmask_b32_e64 v31, v160, 0, vcc
	v_cmp_gt_i32_e32 vcc, v55, v52
	v_lshlrev_b32_e32 v53, 5, v37
	v_cmp_lt_i32_e64 s[8:9], v37, v41
	v_cndmask_b32_e64 v55, v160, 0, vcc
	v_lshlrev_b32_e32 v41, 5, v48
	v_lshlrev_b32_e32 v37, 6, v37
	v_or_b32_e32 v45, v45, v35
	v_lshlrev_b32_e32 v48, 6, v48
	v_or_b32_e32 v35, v49, v35
	v_readlane_b32 s10, v254, 23
	v_readlane_b32 s11, v254, 24
	v_readlane_b32 s16, v254, 29
	v_readlane_b32 s17, v254, 30
	v_readlane_b32 s18, v254, 31
	v_readlane_b32 s19, v254, 32
	v_readlane_b32 s20, v254, 33
	v_readlane_b32 s21, v254, 34
	v_readlane_b32 s22, v254, 35
	v_readlane_b32 s23, v254, 36
	v_add_u32_e32 v43, s0, v34
	v_add_u32_e32 v36, 0, v36
	v_add_u32_e32 v96, 0, v34
	v_mul_u32_u24_e32 v47, 48, v46
	v_mul_u32_u24_e32 v51, 48, v50
	v_pack_b32_f16 v31, v31, v55
	v_pack_b32_f16 v30, v30, v56
	v_pack_b32_f16 v29, v29, v54
	v_mul_u32_u24_e32 v44, 0x90, v44
	v_mul_u32_u24_e32 v103, 0x90, v91
	v_add_u32_e32 v104, v38, v37
	v_mul_u32_u24_e32 v54, 0x90, v45
	v_or_b32_e32 v55, 2, v45
	v_or_b32_e32 v56, 3, v45
	v_add_u32_e32 v105, v38, v48
	v_mul_u32_u24_e32 v38, 0x90, v35
	v_or_b32_e32 v49, 2, v35
	v_or_b32_e32 v57, 3, v35
	v_sub_u32_e32 v115, 0xbf, v32
	v_add_u32_e32 v116, 64, v32
	v_mov_b32_e32 v32, 0
	v_lshl_add_u32 v95, v72, 1, 0
	v_add_u32_e32 v102, 16, v101
	v_mul_u32_u24_e32 v106, 0x90, v46
	v_add_u32_e32 v107, v42, v37
	v_mul_u32_u24_e32 v108, 0x90, v50
	v_add_u32_e32 v109, v42, v48
	v_cmp_gt_i32_e64 s[10:11], v45, v52
	v_cmp_lt_i32_e64 s[12:13], v45, v52
	v_cmp_gt_i32_e64 s[14:15], v55, v52
	v_cmp_gt_i32_e64 s[16:17], v56, v52
	v_cmp_gt_i32_e64 s[18:19], v35, v52
	v_cmp_lt_i32_e64 s[20:21], v35, v52
	v_cmp_gt_i32_e64 s[22:23], v49, v52
	v_cmp_gt_i32_e64 s[24:25], v57, v52
	v_add_u32_e32 v110, v43, v37
	v_add_u32_e32 v111, v43, v48
	s_mov_b32 s26, 0
	v_sub_u32_e32 v112, 0, v91
	v_add_u32_e32 v113, 64, v33
	v_sub_u32_e32 v114, 0xbf, v33
	v_add_u32_e32 v117, v40, v47
	v_add_u32_e32 v118, v39, v54
	v_add_u32_e32 v119, v40, v51
	v_add_u32_e32 v120, v39, v38
	v_lshlrev_b32_e32 v84, 1, v2
	v_add_u32_e32 v121, v78, v44
	v_add_u32_e32 v122, v100, v53
	v_add_u32_e32 v123, v100, v41
	v_add_u32_e32 v124, v36, v34
	v_add_u32_e32 v125, v96, v103
	s_mov_b32 s27, 0
	s_mov_b32 s28, 0
	v_mov_b32_e32 v33, v32
	v_mov_b32_e32 v34, v32
	v_mov_b32_e32 v35, v32
	v_mov_b32_e32 v44, v32
	v_mov_b32_e32 v45, v32
	v_mov_b32_e32 v46, v32
	v_mov_b32_e32 v47, v32
	v_mov_b32_e32 v40, v32
	v_mov_b32_e32 v41, v32
	v_mov_b32_e32 v42, v32
	v_mov_b32_e32 v43, v32
	v_mov_b32_e32 v36, v32
	v_mov_b32_e32 v37, v32
	v_mov_b32_e32 v38, v32
	v_mov_b32_e32 v39, v32
	s_waitcnt vmcnt(0)
	s_branch .LBB0_328

.LBB0_328:
	v_cvt_pk_f16_f32 v49, v46, v47
	v_cvt_pk_f16_f32 v48, v44, v45
	v_cvt_pk_f16_f32 v51, v34, v35
	v_cvt_pk_f16_f32 v50, v32, v33
	s_waitcnt lgkmcnt(0)
	s_barrier
	s_waitcnt vmcnt(8)
	ds_write_b128 v92, v[4:7]
	s_waitcnt vmcnt(7)
	ds_write_b128 v92, v[8:11] offset:9216
	s_waitcnt vmcnt(6)
	ds_write_b16 v98, v12 offset:55296
	s_waitcnt vmcnt(5)
	ds_write_b16 v99, v16 offset:56448
	ds_write_b16_d16_hi v98, v12 offset:55440
	ds_write_b16_d16_hi v99, v16 offset:56592
	ds_write_b16 v98, v13 offset:55584
	ds_write_b16 v99, v17 offset:56736
	ds_write_b16_d16_hi v98, v13 offset:55728
	ds_write_b16_d16_hi v99, v17 offset:56880
	ds_write_b16 v98, v14 offset:55872
	ds_write_b16 v99, v18 offset:57024
	ds_write_b16_d16_hi v98, v14 offset:56016
	ds_write_b16_d16_hi v99, v18 offset:57168
	ds_write_b16 v98, v15 offset:56160
	ds_write_b16 v99, v19 offset:57312
	ds_write_b16_d16_hi v98, v15 offset:56304
	ds_write_b16_d16_hi v99, v19 offset:57456
	ds_write2_b64 v79, v[48:49], v[50:51] offset1:4
	v_cvt_pk_f16_f32 v49, v42, v43
	v_cvt_pk_f16_f32 v48, v40, v41
	v_cvt_pk_f16_f32 v51, v38, v39
	v_cvt_pk_f16_f32 v50, v36, v37
	v_mov_b32_e32 v52, 0
	v_mov_b32_e32 v53, 0
	v_mov_b32_e32 v54, 0
	v_mov_b32_e32 v55, 0
	ds_write2_b64 v79, v[48:49], v[50:51] offset0:8 offset1:12
	s_and_saveexec_b64 s[0:1], s[4:5]
	ds_read_b128 v[52:55], v117
	s_or_b64 exec, exec, s[0:1]
	s_waitcnt vmcnt(4)
	v_cndmask_b32_e64 v51, 0, v23, s[4:5]
	v_cndmask_b32_e64 v50, 0, v22, s[4:5]
	v_cndmask_b32_e64 v49, 0, v21, s[4:5]
	v_cndmask_b32_e64 v48, 0, v20, s[4:5]
	ds_read_b128 v[56:59], v104
	s_waitcnt lgkmcnt(1)
	v_mfma_f32_16x16x32_f16 v[52:55], v[52:55], v[48:51], 0
	s_waitcnt lgkmcnt(0)
	s_nop 6
	v_add_f32_e32 v2, v52, v56
	v_min_f32_e32 v52, 0, v2
	v_mul_f32_e64 v2, |v2|, s89
	v_exp_f32_e32 v2, v2
	s_nop 0
	v_add_f32_e32 v2, 1.0, v2
	v_cmp_gt_f32_e32 vcc, s88, v2
	s_nop 1
	v_cndmask_b32_e64 v56, 0, 32, vcc
	v_ldexp_f32 v2, v2, v56
	v_log_f32_e32 v2, v2
	s_nop 0
	v_mul_f32_e32 v56, 0x3f317217, v2
	v_fma_f32 v56, v2, s35, -v56
	v_fmac_f32_e32 v56, 0x3377d1cf, v2
	v_fmac_f32_e32 v56, 0x3f317217, v2
	v_cmp_lt_f32_e64 s[0:1], |v2|, s93
	s_nop 1
	v_cndmask_b32_e64 v2, v2, v56, s[0:1]
	v_cndmask_b32_e32 v56, 0, v161, vcc
	v_sub_f32_e32 v2, v2, v56
	v_sub_f32_e32 v2, v52, v2
	v_mul_f32_e32 v2, 0x3d800000, v2
	v_max_f32_e32 v2, -1.0, v2
	v_cvt_f16_f32_e32 v2, v2
	ds_write_b16 v118, v2
	v_add_f32_e32 v2, v53, v57
	v_min_f32_e32 v52, 0, v2
	v_mul_f32_e64 v2, |v2|, s89
	v_exp_f32_e32 v2, v2
	s_nop 0
	v_add_f32_e32 v2, 1.0, v2
	v_cmp_gt_f32_e32 vcc, s88, v2
	s_nop 1
	v_cndmask_b32_e64 v53, 0, 32, vcc
	v_ldexp_f32 v2, v2, v53
	v_log_f32_e32 v2, v2
	s_nop 0
	v_mul_f32_e32 v53, 0x3f317217, v2
	v_fma_f32 v53, v2, s35, -v53
	v_fmac_f32_e32 v53, 0x3377d1cf, v2
	v_fmac_f32_e32 v53, 0x3f317217, v2
	v_cmp_lt_f32_e64 s[0:1], |v2|, s93
	s_nop 1
	v_cndmask_b32_e64 v2, v2, v53, s[0:1]
	v_cndmask_b32_e32 v53, 0, v161, vcc
	v_sub_f32_e32 v2, v2, v53
	v_sub_f32_e32 v2, v52, v2
	v_mul_f32_e32 v2, 0x3d800000, v2
	v_max_f32_e32 v2, -1.0, v2
	v_cvt_f16_f32_e32 v2, v2
	ds_write_b16 v118, v2 offset:144
	v_add_f32_e32 v2, v54, v58
	v_min_f32_e32 v52, 0, v2
	v_mul_f32_e64 v2, |v2|, s89
	v_exp_f32_e32 v2, v2
	v_mov_b32_e32 v54, 0
	v_add_f32_e32 v2, 1.0, v2
	v_cmp_gt_f32_e32 vcc, s88, v2
	s_nop 1
	v_cndmask_b32_e64 v53, 0, 32, vcc
	v_ldexp_f32 v2, v2, v53
	v_log_f32_e32 v2, v2
	s_nop 0
	v_mul_f32_e32 v53, 0x3f317217, v2
	v_fma_f32 v53, v2, s35, -v53
	v_fmac_f32_e32 v53, 0x3377d1cf, v2
	v_fmac_f32_e32 v53, 0x3f317217, v2
	v_cmp_lt_f32_e64 s[0:1], |v2|, s93
	s_nop 1
	v_cndmask_b32_e64 v2, v2, v53, s[0:1]
	v_cndmask_b32_e32 v53, 0, v161, vcc
	v_sub_f32_e32 v2, v2, v53
	v_sub_f32_e32 v2, v52, v2
	v_mul_f32_e32 v2, 0x3d800000, v2
	v_max_f32_e32 v2, -1.0, v2
	v_cvt_f16_f32_e32 v2, v2
	ds_write_b16 v118, v2 offset:288
	v_add_f32_e32 v2, v55, v59
	v_min_f32_e32 v52, 0, v2
	v_mul_f32_e64 v2, |v2|, s89
	v_exp_f32_e32 v2, v2
	v_mov_b32_e32 v55, 0
	v_add_f32_e32 v2, 1.0, v2
	v_cmp_gt_f32_e32 vcc, s88, v2
	s_nop 1
	v_cndmask_b32_e64 v53, 0, 32, vcc
	v_ldexp_f32 v2, v2, v53
	v_log_f32_e32 v2, v2
	s_nop 0
	v_mul_f32_e32 v53, 0x3f317217, v2
	v_fma_f32 v53, v2, s35, -v53
	v_fmac_f32_e32 v53, 0x3377d1cf, v2
	v_fmac_f32_e32 v53, 0x3f317217, v2
	v_cmp_lt_f32_e64 s[0:1], |v2|, s93
	s_nop 1
	v_cndmask_b32_e64 v2, v2, v53, s[0:1]
	v_cndmask_b32_e32 v53, 0, v161, vcc
	v_sub_f32_e32 v2, v2, v53
	v_sub_f32_e32 v2, v52, v2
	v_mul_f32_e32 v2, 0x3d800000, v2
	v_max_f32_e32 v2, -1.0, v2
	v_cvt_f16_f32_e32 v2, v2
	v_mov_b32_e32 v52, 0
	v_mov_b32_e32 v53, 0
	ds_write_b16 v118, v2 offset:432
	s_and_saveexec_b64 s[0:1], s[4:5]
	ds_read_b128 v[52:55], v119
	s_or_b64 exec, exec, s[0:1]
	s_waitcnt lgkmcnt(0)
	v_mfma_f32_16x16x32_f16 v[48:51], v[52:55], v[48:51], 0
	ds_read_b128 v[52:55], v105
	s_cmp_gt_u32 s28, 2
	s_waitcnt lgkmcnt(0)
	s_nop 4
	v_add_f32_e32 v2, v48, v52
	v_min_f32_e32 v48, 0, v2
	v_mul_f32_e64 v2, |v2|, s89
	v_exp_f32_e32 v2, v2
	s_nop 0
	v_add_f32_e32 v2, 1.0, v2
	v_cmp_gt_f32_e32 vcc, s88, v2
	s_nop 1
	v_cndmask_b32_e64 v52, 0, 32, vcc
	v_ldexp_f32 v2, v2, v52
	v_log_f32_e32 v2, v2
	s_nop 0
	v_mul_f32_e32 v52, 0x3f317217, v2
	v_fma_f32 v52, v2, s35, -v52
	v_fmac_f32_e32 v52, 0x3377d1cf, v2
	v_fmac_f32_e32 v52, 0x3f317217, v2
	v_cmp_lt_f32_e64 s[0:1], |v2|, s93
	s_nop 1
	v_cndmask_b32_e64 v2, v2, v52, s[0:1]
	v_cndmask_b32_e32 v52, 0, v161, vcc
	v_sub_f32_e32 v2, v2, v52
	v_sub_f32_e32 v2, v48, v2
	v_mul_f32_e32 v2, 0x3d800000, v2
	v_max_f32_e32 v2, -1.0, v2
	v_cvt_f16_f32_e32 v2, v2
	ds_write_b16 v120, v2
	v_add_f32_e32 v2, v49, v53
	v_min_f32_e32 v48, 0, v2
	v_mul_f32_e64 v2, |v2|, s89
	v_exp_f32_e32 v2, v2
	s_nop 0
	v_add_f32_e32 v2, 1.0, v2
	v_cmp_gt_f32_e32 vcc, s88, v2
	s_nop 1
	v_cndmask_b32_e64 v49, 0, 32, vcc
	v_ldexp_f32 v2, v2, v49
	v_log_f32_e32 v2, v2
	s_nop 0
	v_mul_f32_e32 v49, 0x3f317217, v2
	v_fma_f32 v49, v2, s35, -v49
	v_fmac_f32_e32 v49, 0x3377d1cf, v2
	v_fmac_f32_e32 v49, 0x3f317217, v2
	v_cmp_lt_f32_e64 s[0:1], |v2|, s93
	s_nop 1
	v_cndmask_b32_e64 v2, v2, v49, s[0:1]
	v_cndmask_b32_e32 v49, 0, v161, vcc
	v_sub_f32_e32 v2, v2, v49
	v_sub_f32_e32 v2, v48, v2
	v_mul_f32_e32 v2, 0x3d800000, v2
	v_max_f32_e32 v2, -1.0, v2
	v_cvt_f16_f32_e32 v2, v2
	ds_write_b16 v120, v2 offset:144
	v_add_f32_e32 v2, v50, v54
	v_min_f32_e32 v48, 0, v2
	v_mul_f32_e64 v2, |v2|, s89
	v_exp_f32_e32 v2, v2
	s_nop 0
	v_add_f32_e32 v2, 1.0, v2
	v_cmp_gt_f32_e32 vcc, s88, v2
	s_nop 1
	v_cndmask_b32_e64 v49, 0, 32, vcc
	v_ldexp_f32 v2, v2, v49
	v_log_f32_e32 v2, v2
	s_nop 0
	v_mul_f32_e32 v49, 0x3f317217, v2
	v_fma_f32 v49, v2, s35, -v49
	v_fmac_f32_e32 v49, 0x3377d1cf, v2
	v_fmac_f32_e32 v49, 0x3f317217, v2
	v_cmp_lt_f32_e64 s[0:1], |v2|, s93
	s_nop 1
	v_cndmask_b32_e64 v2, v2, v49, s[0:1]
	v_cndmask_b32_e32 v49, 0, v161, vcc
	v_sub_f32_e32 v2, v2, v49
	v_sub_f32_e32 v2, v48, v2
	v_mul_f32_e32 v2, 0x3d800000, v2
	v_max_f32_e32 v2, -1.0, v2
	v_cvt_f16_f32_e32 v2, v2
	ds_write_b16 v120, v2 offset:288
	v_add_f32_e32 v2, v51, v55
	v_min_f32_e32 v48, 0, v2
	v_mul_f32_e64 v2, |v2|, s89
	v_exp_f32_e32 v2, v2
	s_nop 0
	v_add_f32_e32 v2, 1.0, v2
	v_cmp_gt_f32_e32 vcc, s88, v2
	s_nop 1
	v_cndmask_b32_e64 v49, 0, 32, vcc
	v_ldexp_f32 v2, v2, v49
	v_log_f32_e32 v2, v2
	s_nop 0
	v_mul_f32_e32 v49, 0x3f317217, v2
	v_fma_f32 v49, v2, s35, -v49
	v_fmac_f32_e32 v49, 0x3377d1cf, v2
	v_fmac_f32_e32 v49, 0x3f317217, v2
	v_cmp_lt_f32_e64 s[0:1], |v2|, s93
	s_nop 1
	v_cndmask_b32_e64 v2, v2, v49, s[0:1]
	v_cndmask_b32_e32 v49, 0, v161, vcc
	v_sub_f32_e32 v2, v2, v49
	v_sub_f32_e32 v2, v48, v2
	v_mul_f32_e32 v2, 0x3d800000, v2
	v_max_f32_e32 v2, -1.0, v2
	v_cvt_f16_f32_e32 v2, v2
	ds_write_b16 v120, v2 offset:432
	s_waitcnt lgkmcnt(0)
	s_barrier
	s_cbranch_scc1 .LBB0_336
	v_add_u32_e32 v2, s26, v116
	v_add_u32_e32 v4, s27, v115
	v_readlane_b32 s52, v254, 21
	v_cndmask_b32_e64 v2, v4, v2, s[2:3]
	v_readlane_b32 s54, v254, 23
	v_readlane_b32 s55, v254, 24
	v_add_u32_e32 v2, v2, v89
	v_mov_b32_e32 v81, v3
	v_mov_b64_e32 v[4:5], s[54:55]
	v_mad_i64_i32 v[12:13], s[0:1], v2, s87, v[4:5]
	v_lshl_add_u64 v[4:5], v[0:1], 1, v[12:13]
	v_lshlrev_b32_e32 v2, 1, v73
	v_lshl_add_u64 v[12:13], v[12:13], 0, v[80:81]
	v_mov_b32_e32 v85, v3
	v_lshl_add_u64 v[8:9], v[4:5], 0, v[2:3]
	v_lshl_add_u64 v[16:17], v[12:13], 0, v[84:85]
	global_load_dwordx4 v[4:7], v[8:9], off
	s_nop 0
	global_load_dwordx4 v[8:11], v[8:9], off offset:768
	s_nop 0
	global_load_dwordx4 v[12:15], v[16:17], off offset:1536
	s_nop 0
	global_load_dwordx4 v[16:19], v[16:17], off offset:1552
	v_readlane_b32 s53, v254, 22
	v_readlane_b32 s56, v254, 25
	v_readlane_b32 s57, v254, 26
	v_readlane_b32 s58, v254, 27
	v_readlane_b32 s59, v254, 28
	v_readlane_b32 s60, v254, 29
	v_readlane_b32 s61, v254, 30
	v_readlane_b32 s62, v254, 31
	v_readlane_b32 s63, v254, 32
	v_readlane_b32 s64, v254, 33
	v_readlane_b32 s65, v254, 34
	v_readlane_b32 s66, v254, 35
	v_readlane_b32 s67, v254, 36
	s_and_saveexec_b64 s[0:1], s[4:5]
	s_cbranch_execz .LBB0_335
	v_add_u32_e32 v2, s26, v113
	v_add_u32_e32 v20, s27, v114
	v_readlane_b32 s52, v254, 21
	v_cndmask_b32_e64 v2, v20, v2, s[2:3]
	v_readlane_b32 s54, v254, 23
	v_readlane_b32 s55, v254, 24
	v_add_u32_e32 v2, v2, v89
	v_readlane_b32 s53, v254, 22
	v_mov_b64_e32 v[20:21], s[54:55]
	v_mad_i64_i32 v[20:21], s[30:31], v2, s87, v[20:21]
	v_lshl_add_u64 v[20:21], v[74:75], 1, v[20:21]
	v_add_co_u32_e32 v20, vcc, 0x1000, v20
	v_readlane_b32 s56, v254, 25
	s_nop 0
	v_addc_co_u32_e32 v21, vcc, 0, v21, vcc
	global_load_dwordx4 v[20:23], v[20:21], off offset:512
	v_readlane_b32 s57, v254, 26
	v_readlane_b32 s58, v254, 27
	v_readlane_b32 s59, v254, 28
	v_readlane_b32 s60, v254, 29
	v_readlane_b32 s61, v254, 30
	v_readlane_b32 s62, v254, 31
	v_readlane_b32 s63, v254, 32
	v_readlane_b32 s64, v254, 33
	v_readlane_b32 s65, v254, 34
	v_readlane_b32 s66, v254, 35
	v_readlane_b32 s67, v254, 36

.LBB0_420:
	s_or_b64 exec, exec, s[0:1]
	v_readlane_b32 s8, v254, 21
	v_readlane_b32 s13, v254, 26
	v_readlane_b32 s15, v254, 28
	v_lshlrev_b32_e32 v51, 2, v46
	v_readlane_b32 s12, v254, 25
	v_readlane_b32 s14, v254, 27
	v_mov_b32_e32 v45, s15
	v_mov_b32_e32 v46, s13
	v_cndmask_b32_e64 v55, v45, v46, s[2:3]
	v_mov_b32_e32 v45, s14
	v_mov_b32_e32 v46, s12
	v_cndmask_b32_e64 v54, v45, v46, s[2:3]
	v_mul_lo_u32 v45, v82, s92
	v_add_u32_e32 v46, 0, v45
	s_movk_i32 s0, 0xff72
	v_mad_u64_u32 v[72:73], s[0:1], v82, s0, v[46:47]
	v_lshlrev_b32_e32 v1, 3, v47
	v_mul_lo_u32 v43, v43, s92
	v_readlane_b32 s0, v255, 33
	v_lshlrev_b32_e32 v41, 1, v41
	v_and_b32_e32 v56, 2, v41
	v_add3_u32 v73, s0, v43, v0
	s_add_i32 s0, 0, 0x1e400
	v_lshlrev_b32_e32 v41, 1, v53
	v_lshlrev_b32_e32 v45, 1, v80
	v_readlane_b32 s1, v255, 34
	v_ashrrev_i32_e32 v59, 7, v40
	v_readlane_b32 s6, v255, 35
	v_lshlrev_b32_e32 v74, 1, v2
	v_xor_b32_e32 v2, 16, v1
	v_readlane_b32 s9, v254, 22
	v_add_u32_e32 v57, s0, v50
	v_add3_u32 v53, s1, v41, v45
	v_readlane_b32 s0, v255, 31
	v_lshlrev_b32_e32 v41, 4, v59
	v_lshl_add_u32 v45, v59, 12, s6
	v_lshlrev_b32_e32 v60, 8, v80
	v_mov_b32_e32 v75, v3
	v_lshl_add_u32 v88, v2, 1, v46
	v_and_b32_e32 v2, 2, v40
	v_mul_u32_u24_e32 v89, 0x480, v47
	v_add_u32_e32 v58, s0, v50
	v_add_u32_e32 v84, s1, v50
	v_add3_u32 v60, v45, v60, v50
	v_cmp_eq_u32_e32 vcc, 3, v59
	v_cmp_eq_u32_e64 s[0:1], 15, v80
	v_lshlrev_b32_e32 v45, 8, v82
	v_lshlrev_b32_e32 v62, 2, v1
	v_add_u32_e32 v63, 0, v43
	v_lshl_add_u64 v[54:55], v[54:55], 0, v[74:75]
	v_ashrrev_i32_e32 v43, 31, v42
	v_cmp_eq_u32_e64 s[8:9], 0, v2
	v_lshlrev_b32_e32 v2, 1, v89
	v_lshlrev_b32_e32 v40, 1, v82
	v_or_b32_e32 v69, v41, v80
	s_and_b64 s[76:77], vcc, s[0:1]
	v_add3_u32 v85, s6, v45, v62
	v_lshl_add_u64 v[42:43], v[42:43], 1, v[54:55]
	v_mov_b32_e32 v45, v3
	v_add3_u32 v91, 0, v2, v40
	v_or_b32_e32 v40, 2, v0
	v_cmp_gt_i32_e32 vcc, v0, v69
	v_lshl_add_u64 v[76:77], v[42:43], 0, v[44:45]
	v_mul_lo_u32 v41, v69, s92
	v_cndmask_b32_e64 v44, v160, 0, vcc
	v_cmp_lt_i32_e32 vcc, v69, v40
	v_or_b32_e32 v42, 3, v0
	v_add3_u32 v92, 0, v41, v0
	v_cndmask_b32_e64 v40, v160, 0, vcc
	v_cmp_lt_i32_e32 vcc, v0, v69
	v_or_b32_e32 v41, 4, v0
	v_lshl_add_u32 v83, v1, 1, v46
	v_cndmask_b32_e32 v45, 0, v160, vcc
	v_cmp_gt_i32_e32 vcc, v42, v69
	v_or_b32_e32 v43, 5, v0
	v_or_b32_e32 v42, 6, v0
	v_cndmask_b32_e64 v46, v160, 0, vcc
	v_cmp_gt_i32_e32 vcc, v41, v69
	v_cmp_gt_u32_e64 s[6:7], 4, v47
	v_add_u32_e32 v79, 38, v0
	v_cndmask_b32_e64 v41, v160, 0, vcc
	v_cmp_gt_i32_e32 vcc, v43, v69
	v_or_b32_e32 v43, 7, v0
	v_or_b32_e32 v65, 1, v56
	v_cndmask_b32_e64 v47, v160, 0, vcc
	v_cmp_gt_i32_e32 vcc, v42, v69
	v_readlane_b32 s10, v254, 23
	v_readlane_b32 s11, v254, 24
	v_cndmask_b32_e64 v42, v160, 0, vcc
	v_cmp_gt_i32_e32 vcc, v43, v69
	v_readlane_b32 s0, v255, 37
	v_add_u32_e32 v90, v72, v2
	v_cndmask_b32_e64 v43, v160, 0, vcc
	v_pack_b32_f16 v43, v42, v43
	v_pack_b32_f16 v42, v41, v47
	v_pack_b32_f16 v41, v40, v46
	v_pack_b32_f16 v40, v44, v45
	v_or_b32_e32 v44, 32, v0
	v_cmp_gt_i32_e32 vcc, v44, v69
	v_add_u32_e32 v45, 33, v0
	v_add_u32_e32 v46, 34, v0
	v_cndmask_b32_e64 v44, v160, 0, vcc
	v_cmp_gt_i32_e32 vcc, v45, v69
	v_add_u32_e32 v47, 36, v0
	v_lshlrev_b32_e32 v2, 4, v56
	v_cndmask_b32_e64 v75, v160, 0, vcc
	v_cmp_gt_i32_e32 vcc, v46, v69
	v_add_u32_e32 v46, 35, v0
	v_lshlrev_b32_e32 v66, 4, v65
	v_cndmask_b32_e64 v45, v160, 0, vcc
	v_cmp_gt_i32_e32 vcc, v46, v69
	v_or_b32_e32 v55, v2, v80
	v_or_b32_e32 v67, v66, v80
	v_cndmask_b32_e64 v78, v160, 0, vcc
	v_cmp_gt_i32_e32 vcc, v47, v69
	v_add_u32_e32 v47, 37, v0
	v_pack_b32_f16 v44, v44, v75
	v_cndmask_b32_e64 v46, v160, 0, vcc
	v_cmp_gt_i32_e32 vcc, v47, v69
	v_cmp_le_i32_e64 s[10:11], v56, v59
	v_lshlrev_b32_e32 v75, 5, v56
	v_cndmask_b32_e64 v93, v160, 0, vcc
	v_cmp_gt_i32_e32 vcc, v79, v69
	v_add_u32_e32 v79, 39, v0
	v_pack_b32_f16 v46, v46, v93
	v_cndmask_b32_e64 v47, v160, 0, vcc
	v_cmp_gt_i32_e32 vcc, v79, v69
	v_add_u32_e32 v93, s0, v62
	v_or_b32_e32 v62, 1, v1
	v_cndmask_b32_e64 v79, v160, 0, vcc
	v_cmp_lt_i32_e64 s[12:13], v56, v59
	v_lshlrev_b32_e32 v59, 5, v65
	v_lshlrev_b32_e32 v56, 6, v56
	v_or_b32_e32 v2, v2, v51
	v_lshlrev_b32_e32 v65, 6, v65
	v_or_b32_e32 v51, v66, v51
	v_readlane_b32 s16, v254, 29
	v_readlane_b32 s17, v254, 30
	v_readlane_b32 s18, v254, 31
	v_readlane_b32 s19, v254, 32
	v_readlane_b32 s20, v254, 33
	v_readlane_b32 s21, v254, 34
	v_readlane_b32 s22, v254, 35
	v_readlane_b32 s23, v254, 36
	v_add_u32_e32 v61, s0, v50
	v_add_u32_e32 v87, 0, v50
	v_and_b32_e32 v54, 8, v1
	v_mul_u32_u24_e32 v64, 48, v55
	v_mul_u32_u24_e32 v68, 48, v67
	v_pack_b32_f16 v47, v47, v79
	v_pack_b32_f16 v45, v45, v78
	v_mul_u32_u24_e32 v62, 0x90, v62
	v_mul_u32_u24_e32 v95, 0x90, v80
	v_add_u32_e32 v96, v57, v56
	v_mul_u32_u24_e32 v78, 0x90, v2
	v_or_b32_e32 v79, 2, v2
	v_or_b32_e32 v102, 3, v2
	v_add_u32_e32 v97, v57, v65
	v_mul_u32_u24_e32 v57, 0x90, v51
	v_or_b32_e32 v66, 2, v51
	v_or_b32_e32 v103, 3, v51
	v_lshl_add_u32 v86, v0, 1, 0
	s_mov_b32 s78, 0
	v_add_u32_e32 v94, 16, v93
	v_mul_u32_u24_e32 v98, 0x90, v55
	v_add_u32_e32 v99, v60, v56
	v_mul_u32_u24_e32 v100, 0x90, v67
	v_add_u32_e32 v101, v60, v65
	v_cmp_gt_i32_e64 s[14:15], v2, v69
	v_cmp_lt_i32_e64 s[16:17], v2, v69
	v_cmp_gt_i32_e64 s[18:19], v79, v69
	v_cmp_gt_i32_e64 s[20:21], v102, v69
	v_cmp_gt_i32_e64 s[22:23], v51, v69
	v_cmp_lt_i32_e64 s[24:25], v51, v69
	v_cmp_gt_i32_e64 s[26:27], v66, v69
	v_cmp_gt_i32_e64 s[28:29], v103, v69
	v_add_u32_e32 v102, v61, v56
	v_add_u32_e32 v103, v61, v65
	v_sub_u32_e32 v104, 0, v80
	v_sub_u32_e32 v105, 0, v82
	v_add_u32_e32 v106, 64, v49
	v_sub_u32_e32 v107, 0x7bf, v49
	v_add_u32_e32 v108, v58, v64
	v_add_u32_e32 v109, v53, v78
	v_add_u32_e32 v110, v58, v68
	v_add_u32_e32 v111, v53, v57
	v_lshlrev_b32_e32 v2, 1, v52
	v_lshlrev_b32_e32 v78, 1, v48
	v_lshlrev_b32_e32 v112, 2, v54
	v_add_u32_e32 v113, v72, v62
	v_add_u32_e32 v114, v92, v75
	v_add_u32_e32 v115, v92, v59
	v_add_u32_e32 v116, v63, v50
	v_add_u32_e32 v117, v87, v95
	s_mov_b32 s79, 0
	s_mov_b32 s30, 0
	s_waitcnt vmcnt(0)
	s_branch .LBB0_422

.LBB0_422:
	s_waitcnt vmcnt(16)
	v_cvt_pk_f16_f32 v49, v10, v11
	v_cvt_pk_f16_f32 v48, v8, v9
	s_waitcnt vmcnt(12)
	v_cvt_pk_f16_f32 v51, v6, v7
	v_cvt_pk_f16_f32 v50, v4, v5
	s_waitcnt lgkmcnt(0)
	s_barrier
	s_waitcnt vmcnt(8)
	ds_write_b128 v83, v[20:23]
	s_waitcnt vmcnt(7)
	ds_write_b128 v83, v[24:27] offset:9216
	s_waitcnt vmcnt(6)
	ds_write_b16 v90, v28 offset:55296
	s_waitcnt vmcnt(5)
	ds_write_b16 v91, v32 offset:56448
	ds_write_b16_d16_hi v90, v28 offset:55440
	ds_write_b16_d16_hi v91, v32 offset:56592
	ds_write_b16 v90, v29 offset:55584
	ds_write_b16 v91, v33 offset:56736
	ds_write_b16_d16_hi v90, v29 offset:55728
	ds_write_b16_d16_hi v91, v33 offset:56880
	ds_write_b16 v90, v30 offset:55872
	ds_write_b16 v91, v34 offset:57024
	ds_write_b16_d16_hi v90, v30 offset:56016
	ds_write_b16_d16_hi v91, v34 offset:57168
	ds_write_b16 v90, v31 offset:56160
	ds_write_b16 v91, v35 offset:57312
	ds_write_b16_d16_hi v90, v31 offset:56304
	ds_write_b16_d16_hi v91, v35 offset:57456
	ds_write2_b64 v73, v[48:49], v[50:51] offset1:4
	v_cvt_pk_f16_f32 v49, v18, v19
	v_cvt_pk_f16_f32 v48, v16, v17
	v_cvt_pk_f16_f32 v51, v14, v15
	v_cvt_pk_f16_f32 v50, v12, v13
	ds_write2_b64 v73, v[48:49], v[50:51] offset0:8 offset1:12
	v_mov_b32_e32 v48, 0
	v_mov_b32_e32 v56, 0
	v_mov_b32_e32 v57, 0
	v_mov_b32_e32 v58, 0
	v_mov_b32_e32 v59, 0
	s_and_saveexec_b64 s[0:1], s[4:5]
	ds_read_b128 v[56:59], v108
	s_or_b64 exec, exec, s[0:1]
	s_waitcnt vmcnt(4)
	v_cndmask_b32_e64 v55, 0, v39, s[4:5]
	v_cndmask_b32_e64 v54, 0, v38, s[4:5]
	v_cndmask_b32_e64 v53, 0, v37, s[4:5]
	v_cndmask_b32_e64 v52, 0, v36, s[4:5]
	ds_read_b128 v[60:63], v96
	s_waitcnt lgkmcnt(1)
	v_mfma_f32_16x16x32_f16 v[56:59], v[56:59], v[52:55], 0
	s_waitcnt lgkmcnt(0)
	s_nop 6
	v_add_f32_e32 v49, v56, v60
	v_min_f32_e32 v50, 0, v49
	v_mul_f32_e64 v49, |v49|, s89
	v_exp_f32_e32 v49, v49
	s_nop 0
	v_add_f32_e32 v49, 1.0, v49
	v_cmp_gt_f32_e32 vcc, s88, v49
	s_nop 1
	v_cndmask_b32_e64 v51, 0, 32, vcc
	v_ldexp_f32 v49, v49, v51
	v_log_f32_e32 v49, v49
	s_nop 0
	v_mul_f32_e32 v51, 0x3f317217, v49
	v_fma_f32 v51, v49, s35, -v51
	v_fmac_f32_e32 v51, 0x3377d1cf, v49
	v_fmac_f32_e32 v51, 0x3f317217, v49
	v_cmp_lt_f32_e64 s[0:1], |v49|, s93
	s_nop 1
	v_cndmask_b32_e64 v49, v49, v51, s[0:1]
	v_cndmask_b32_e32 v51, 0, v161, vcc
	v_sub_f32_e32 v49, v49, v51
	v_sub_f32_e32 v49, v50, v49
	v_mul_f32_e32 v49, 0x3d800000, v49
	v_max_f32_e32 v49, -1.0, v49
	v_cvt_f16_f32_e32 v49, v49
	ds_write_b16 v109, v49
	v_add_f32_e32 v49, v57, v61
	v_min_f32_e32 v50, 0, v49
	v_mul_f32_e64 v49, |v49|, s89
	v_exp_f32_e32 v49, v49
	s_nop 0
	v_add_f32_e32 v49, 1.0, v49
	v_cmp_gt_f32_e32 vcc, s88, v49
	s_nop 1
	v_cndmask_b32_e64 v51, 0, 32, vcc
	v_ldexp_f32 v49, v49, v51
	v_log_f32_e32 v49, v49
	s_nop 0
	v_mul_f32_e32 v51, 0x3f317217, v49
	v_fma_f32 v51, v49, s35, -v51
	v_fmac_f32_e32 v51, 0x3377d1cf, v49
	v_fmac_f32_e32 v51, 0x3f317217, v49
	v_cmp_lt_f32_e64 s[0:1], |v49|, s93
	s_nop 1
	v_cndmask_b32_e64 v49, v49, v51, s[0:1]
	v_cndmask_b32_e32 v51, 0, v161, vcc
	v_sub_f32_e32 v49, v49, v51
	v_sub_f32_e32 v49, v50, v49
	v_mul_f32_e32 v49, 0x3d800000, v49
	v_max_f32_e32 v49, -1.0, v49
	v_cvt_f16_f32_e32 v49, v49
	ds_write_b16 v109, v49 offset:144
	v_add_f32_e32 v49, v58, v62
	v_min_f32_e32 v50, 0, v49
	v_mul_f32_e64 v49, |v49|, s89
	v_exp_f32_e32 v49, v49
	s_nop 0
	v_add_f32_e32 v49, 1.0, v49
	v_cmp_gt_f32_e32 vcc, s88, v49
	s_nop 1
	v_cndmask_b32_e64 v51, 0, 32, vcc
	v_ldexp_f32 v49, v49, v51
	v_log_f32_e32 v49, v49
	s_nop 0
	v_mul_f32_e32 v51, 0x3f317217, v49
	v_fma_f32 v51, v49, s35, -v51
	v_fmac_f32_e32 v51, 0x3377d1cf, v49
	v_fmac_f32_e32 v51, 0x3f317217, v49
	v_cmp_lt_f32_e64 s[0:1], |v49|, s93
	s_nop 1
	v_cndmask_b32_e64 v49, v49, v51, s[0:1]
	v_cndmask_b32_e32 v51, 0, v161, vcc
	v_sub_f32_e32 v49, v49, v51
	v_sub_f32_e32 v49, v50, v49
	v_mul_f32_e32 v49, 0x3d800000, v49
	v_max_f32_e32 v49, -1.0, v49
	v_cvt_f16_f32_e32 v49, v49
	ds_write_b16 v109, v49 offset:288
	v_add_f32_e32 v49, v59, v63
	v_min_f32_e32 v50, 0, v49
	v_mul_f32_e64 v49, |v49|, s89
	v_exp_f32_e32 v49, v49
	s_nop 0
	v_add_f32_e32 v49, 1.0, v49
	v_cmp_gt_f32_e32 vcc, s88, v49
	s_nop 1
	v_cndmask_b32_e64 v51, 0, 32, vcc
	v_ldexp_f32 v49, v49, v51
	v_log_f32_e32 v49, v49
	s_nop 0
	v_mul_f32_e32 v51, 0x3f317217, v49
	v_fma_f32 v51, v49, s35, -v51
	v_fmac_f32_e32 v51, 0x3377d1cf, v49
	v_fmac_f32_e32 v51, 0x3f317217, v49
	v_cmp_lt_f32_e64 s[0:1], |v49|, s93
	s_nop 1
	v_cndmask_b32_e64 v49, v49, v51, s[0:1]
	v_cndmask_b32_e32 v51, 0, v161, vcc
	v_sub_f32_e32 v49, v49, v51
	v_sub_f32_e32 v49, v50, v49
	v_mul_f32_e32 v49, 0x3d800000, v49
	v_max_f32_e32 v49, -1.0, v49
	v_cvt_f16_f32_e32 v49, v49
	v_mov_b32_e32 v50, 0
	v_mov_b32_e32 v51, 0
	ds_write_b16 v109, v49 offset:432
	v_mov_b32_e32 v49, 0
	s_and_saveexec_b64 s[0:1], s[4:5]
	ds_read_b128 v[48:51], v110
	s_or_b64 exec, exec, s[0:1]
	s_waitcnt lgkmcnt(0)
	v_mfma_f32_16x16x32_f16 v[48:51], v[48:51], v[52:55], 0
	ds_read_b128 v[52:55], v97
	s_cmp_gt_u32 s30, 30
	s_waitcnt lgkmcnt(0)
	s_nop 4
	v_add_f32_e32 v48, v48, v52
	v_min_f32_e32 v52, 0, v48
	v_mul_f32_e64 v48, |v48|, s89
	v_exp_f32_e32 v48, v48
	s_nop 0
	v_add_f32_e32 v48, 1.0, v48
	v_cmp_gt_f32_e32 vcc, s88, v48
	s_nop 1
	v_cndmask_b32_e64 v56, 0, 32, vcc
	v_ldexp_f32 v48, v48, v56
	v_log_f32_e32 v48, v48
	s_nop 0
	v_mul_f32_e32 v56, 0x3f317217, v48
	v_fma_f32 v56, v48, s35, -v56
	v_fmac_f32_e32 v56, 0x3377d1cf, v48
	v_fmac_f32_e32 v56, 0x3f317217, v48
	v_cmp_lt_f32_e64 s[0:1], |v48|, s93
	s_nop 1
	v_cndmask_b32_e64 v48, v48, v56, s[0:1]
	v_cndmask_b32_e32 v56, 0, v161, vcc
	v_sub_f32_e32 v48, v48, v56
	v_sub_f32_e32 v48, v52, v48
	v_mul_f32_e32 v48, 0x3d800000, v48
	v_max_f32_e32 v48, -1.0, v48
	v_cvt_f16_f32_e32 v48, v48
	v_add_u32_e32 v56, s79, v105
	ds_write_b16 v111, v48
	v_add_f32_e32 v48, v49, v53
	v_min_f32_e32 v49, 0, v48
	v_mul_f32_e64 v48, |v48|, s89
	v_exp_f32_e32 v48, v48
	s_nop 0
	v_add_f32_e32 v48, 1.0, v48
	v_cmp_gt_f32_e32 vcc, s88, v48
	s_nop 1
	v_cndmask_b32_e64 v52, 0, 32, vcc
	v_ldexp_f32 v48, v48, v52
	v_log_f32_e32 v48, v48
	s_nop 0
	v_mul_f32_e32 v52, 0x3f317217, v48
	v_fma_f32 v52, v48, s35, -v52
	v_fmac_f32_e32 v52, 0x3377d1cf, v48
	v_fmac_f32_e32 v52, 0x3f317217, v48
	v_cmp_lt_f32_e64 s[0:1], |v48|, s93
	s_nop 1
	v_cndmask_b32_e64 v48, v48, v52, s[0:1]
	v_cndmask_b32_e32 v52, 0, v161, vcc
	v_sub_f32_e32 v48, v48, v52
	v_sub_f32_e32 v48, v49, v48
	v_mul_f32_e32 v48, 0x3d800000, v48
	v_max_f32_e32 v48, -1.0, v48
	v_cvt_f16_f32_e32 v48, v48
	ds_write_b16 v111, v48 offset:144
	v_add_f32_e32 v48, v50, v54
	v_min_f32_e32 v49, 0, v48
	v_mul_f32_e64 v48, |v48|, s89
	v_exp_f32_e32 v48, v48
	s_nop 0
	v_add_f32_e32 v48, 1.0, v48
	v_cmp_gt_f32_e32 vcc, s88, v48
	s_nop 1
	v_cndmask_b32_e64 v50, 0, 32, vcc
	v_ldexp_f32 v48, v48, v50
	v_log_f32_e32 v48, v48
	s_nop 0
	v_mul_f32_e32 v50, 0x3f317217, v48
	v_fma_f32 v50, v48, s35, -v50
	v_fmac_f32_e32 v50, 0x3377d1cf, v48
	v_fmac_f32_e32 v50, 0x3f317217, v48
	v_cmp_lt_f32_e64 s[0:1], |v48|, s93
	s_nop 1
	v_cndmask_b32_e64 v48, v48, v50, s[0:1]
	v_cndmask_b32_e32 v50, 0, v161, vcc
	v_sub_f32_e32 v48, v48, v50
	v_sub_f32_e32 v48, v49, v48
	v_mul_f32_e32 v48, 0x3d800000, v48
	v_max_f32_e32 v48, -1.0, v48
	v_cvt_f16_f32_e32 v48, v48
	ds_write_b16 v111, v48 offset:288
	v_add_f32_e32 v48, v51, v55
	v_min_f32_e32 v49, 0, v48
	v_mul_f32_e64 v48, |v48|, s89
	v_exp_f32_e32 v48, v48
	s_nop 0
	v_add_f32_e32 v48, 1.0, v48
	v_cmp_gt_f32_e32 vcc, s88, v48
	s_nop 1
	v_cndmask_b32_e64 v50, 0, 32, vcc
	v_ldexp_f32 v48, v48, v50
	v_log_f32_e32 v48, v48
	s_nop 0
	v_mul_f32_e32 v50, 0x3f317217, v48
	v_fma_f32 v50, v48, s35, -v50
	v_fmac_f32_e32 v50, 0x3377d1cf, v48
	v_fmac_f32_e32 v50, 0x3f317217, v48
	v_cmp_lt_f32_e64 s[0:1], |v48|, s93
	s_nop 1
	v_cndmask_b32_e64 v48, v48, v50, s[0:1]
	v_cndmask_b32_e32 v50, 0, v161, vcc
	v_sub_f32_e32 v48, v48, v50
	v_sub_f32_e32 v48, v49, v48
	v_mul_f32_e32 v48, 0x3d800000, v48
	v_max_f32_e32 v48, -1.0, v48
	v_cvt_f16_f32_e32 v48, v48
	ds_write_b16 v111, v48 offset:432
	s_waitcnt lgkmcnt(0)
	s_barrier
	s_cbranch_scc1 .LBB0_430
	v_add3_u32 v20, v82, s78, 64
	v_add_u32_e32 v21, 0x7bf, v56
	v_readlane_b32 s52, v254, 21
	v_cndmask_b32_e64 v20, v21, v20, s[2:3]
	v_readlane_b32 s54, v254, 23
	v_readlane_b32 s55, v254, 24
	v_add_u32_e32 v22, v20, v81
	v_mov_b32_e32 v75, v3
	v_mov_b64_e32 v[20:21], s[54:55]
	v_mad_i64_i32 v[28:29], s[0:1], v22, s87, v[20:21]
	v_lshl_add_u64 v[20:21], v[28:29], 0, v[2:3]
	v_lshlrev_b32_e32 v22, 1, v1
	v_mov_b32_e32 v23, v3
	v_lshl_add_u64 v[28:29], v[28:29], 0, v[74:75]
	v_mov_b32_e32 v79, v3
	v_lshl_add_u64 v[24:25], v[20:21], 0, v[22:23]
	v_lshl_add_u64 v[32:33], v[28:29], 0, v[78:79]
	global_load_dwordx4 v[20:23], v[24:25], off
	s_nop 0
	global_load_dwordx4 v[24:27], v[24:25], off offset:768
	s_nop 0
	global_load_dwordx4 v[28:31], v[32:33], off offset:1536
	s_nop 0
	global_load_dwordx4 v[32:35], v[32:33], off offset:1552
	v_readlane_b32 s53, v254, 22
	v_readlane_b32 s56, v254, 25
	v_readlane_b32 s57, v254, 26
	v_readlane_b32 s58, v254, 27
	v_readlane_b32 s59, v254, 28
	v_readlane_b32 s60, v254, 29
	v_readlane_b32 s61, v254, 30
	v_readlane_b32 s62, v254, 31
	v_readlane_b32 s63, v254, 32
	v_readlane_b32 s64, v254, 33
	v_readlane_b32 s65, v254, 34
	v_readlane_b32 s66, v254, 35
	v_readlane_b32 s67, v254, 36
	s_and_saveexec_b64 s[0:1], s[4:5]
	s_cbranch_execz .LBB0_429
	v_add_u32_e32 v36, s78, v106
	v_add_u32_e32 v37, s79, v107
	v_readlane_b32 s52, v254, 21
	v_cndmask_b32_e64 v36, v37, v36, s[2:3]
	v_readlane_b32 s54, v254, 23
	v_readlane_b32 s55, v254, 24
	v_add_u32_e32 v38, v36, v81
	v_readlane_b32 s53, v254, 22
	v_mov_b64_e32 v[36:37], s[54:55]
	v_mad_i64_i32 v[36:37], vcc, v38, s87, v[36:37]
	v_lshl_add_u64 v[36:37], v[70:71], 1, v[36:37]
	v_add_co_u32_e32 v36, vcc, 0x1000, v36
	v_readlane_b32 s56, v254, 25
	s_nop 0
	v_addc_co_u32_e32 v37, vcc, 0, v37, vcc
	global_load_dwordx4 v[36:39], v[36:37], off offset:512
	v_readlane_b32 s57, v254, 26
	v_readlane_b32 s58, v254, 27
	v_readlane_b32 s59, v254, 28
	v_readlane_b32 s60, v254, 29
	v_readlane_b32 s61, v254, 30
	v_readlane_b32 s62, v254, 31
	v_readlane_b32 s63, v254, 32
	v_readlane_b32 s64, v254, 33
	v_readlane_b32 s65, v254, 34
	v_readlane_b32 s66, v254, 35
	v_readlane_b32 s67, v254, 36

.LBB0_899:
	s_or_b64 exec, exec, s[0:1]
	v_readlane_b32 s8, v254, 21
	v_readlane_b32 s13, v254, 26
	v_readlane_b32 s15, v254, 28
	v_readlane_b32 s12, v254, 25
	v_readlane_b32 s14, v254, 27
	v_mov_b32_e32 v30, s15
	v_mov_b32_e32 v31, s13
	v_cndmask_b32_e64 v31, v30, v31, s[2:3]
	v_mov_b32_e32 v30, s14
	v_mov_b32_e32 v36, s12
	v_lshlrev_b32_e32 v76, 4, v28
	v_cndmask_b32_e64 v30, v30, v36, s[2:3]
	v_mul_lo_u32 v36, v32, s89
	v_or_b32_e32 v37, v76, v91
	v_add_u32_e32 v36, 0, v36
	s_movk_i32 s0, 0xff72
	v_lshlrev_b32_e32 v73, 3, v25
	v_mad_u64_u32 v[78:79], s[0:1], v32, s0, v[36:37]
	v_lshl_add_u32 v92, v73, 1, v36
	v_mul_lo_u32 v36, v37, s89
	v_readlane_b32 s0, v255, 43
	v_lshlrev_b32_e32 v28, 1, v28
	v_and_b32_e32 v37, 2, v28
	v_add3_u32 v79, s0, v36, v72
	s_add_i32 s0, 0, 0x1e400
	v_add_u32_e32 v38, s0, v34
	v_lshlrev_b32_e32 v28, 1, v29
	v_lshlrev_b32_e32 v29, 1, v91
	v_readlane_b32 s0, v255, 33
	v_ashrrev_i32_e32 v41, 7, v24
	v_readlane_b32 s6, v255, 34
	v_lshlrev_b32_e32 v27, 7, v86
	v_add3_u32 v39, s0, v28, v29
	v_lshl_add_u32 v28, v41, 12, s6
	v_lshlrev_b32_e32 v29, 8, v91
	v_add3_u32 v42, v28, v29, v34
	v_lshlrev_b32_e32 v28, 8, v32
	v_lshlrev_b32_e32 v44, 2, v73
	v_lshlrev_b32_e32 v80, 1, v27
	v_mov_b32_e32 v81, v3
	v_add3_u32 v94, s6, v28, v44
	v_lshl_add_u64 v[28:29], v[30:31], 0, v[80:81]
	v_ashrrev_i32_e32 v77, 31, v76
	v_lshlrev_b32_e32 v24, 4, v41
	v_lshl_add_u64 v[28:29], v[76:77], 1, v[28:29]
	v_mov_b32_e32 v27, v3
	v_mul_u32_u24_e32 v97, 0x480, v25
	v_add_u32_e32 v93, s0, v34
	v_cmp_eq_u32_e32 vcc, 3, v41
	v_cmp_eq_u32_e64 s[0:1], 15, v91
	v_lshl_add_u64 v[82:83], v[28:29], 0, v[26:27]
	v_lshlrev_b32_e32 v25, 1, v97
	v_lshlrev_b32_e32 v26, 1, v32
	v_or_b32_e32 v52, v24, v91
	s_and_b64 s[68:69], vcc, s[0:1]
	v_add_u32_e32 v98, v78, v25
	v_add3_u32 v99, 0, v25, v26
	v_or_b32_e32 v25, 2, v72
	v_mul_lo_u32 v24, v52, s89
	v_cmp_gt_i32_e32 vcc, v72, v52
	v_add3_u32 v100, 0, v24, v72
	v_or_b32_e32 v27, 3, v72
	v_cndmask_b32_e64 v24, v160, 0, vcc
	v_cmp_lt_i32_e32 vcc, v52, v25
	v_or_b32_e32 v26, 4, v72
	v_or_b32_e32 v30, 5, v72
	v_cndmask_b32_e64 v25, v160, 0, vcc
	v_cmp_lt_i32_e32 vcc, v72, v52
	v_or_b32_e32 v31, 7, v72
	v_add_u32_e32 v55, 38, v72
	v_cndmask_b32_e32 v28, 0, v160, vcc
	v_cmp_gt_i32_e32 vcc, v27, v52
	v_or_b32_e32 v27, 6, v72
	v_pack_b32_f16 v24, v24, v28
	v_cndmask_b32_e64 v29, v160, 0, vcc
	v_cmp_gt_i32_e32 vcc, v26, v52
	v_or_b32_e32 v28, 32, v72
	v_pack_b32_f16 v25, v25, v29
	v_cndmask_b32_e64 v26, v160, 0, vcc
	v_cmp_gt_i32_e32 vcc, v30, v52
	v_add_u32_e32 v29, 33, v72
	v_or_b32_e32 v48, 1, v37
	v_cndmask_b32_e64 v30, v160, 0, vcc
	v_cmp_gt_i32_e32 vcc, v27, v52
	v_pack_b32_f16 v26, v26, v30
	v_add_u32_e32 v30, 34, v72
	v_cndmask_b32_e64 v27, v160, 0, vcc
	v_cmp_gt_i32_e32 vcc, v31, v52
	v_lshlrev_b32_e32 v35, 2, v90
	v_readlane_b32 s9, v254, 22
	v_cndmask_b32_e64 v31, v160, 0, vcc
	v_cmp_gt_i32_e32 vcc, v28, v52
	v_pack_b32_f16 v27, v27, v31
	v_add_u32_e32 v31, 36, v72
	v_cndmask_b32_e64 v28, v160, 0, vcc
	v_cmp_gt_i32_e32 vcc, v29, v52
	v_readlane_b32 s0, v255, 37
	v_lshlrev_b32_e32 v45, 4, v37
	v_cndmask_b32_e64 v53, v160, 0, vcc
	v_cmp_gt_i32_e32 vcc, v30, v52
	v_add_u32_e32 v30, 35, v72
	v_lshlrev_b32_e32 v49, 4, v48
	v_cndmask_b32_e64 v29, v160, 0, vcc
	v_cmp_gt_i32_e32 vcc, v30, v52
	v_or_b32_e32 v46, v45, v91
	v_or_b32_e32 v50, v49, v91
	v_cndmask_b32_e64 v54, v160, 0, vcc
	v_cmp_gt_i32_e32 vcc, v31, v52
	v_add_u32_e32 v31, 37, v72
	v_pack_b32_f16 v28, v28, v53
	v_cndmask_b32_e64 v30, v160, 0, vcc
	v_cmp_gt_i32_e32 vcc, v31, v52
	v_add_u32_e32 v101, s0, v44
	v_or_b32_e32 v44, 1, v73
	v_cndmask_b32_e64 v56, v160, 0, vcc
	v_cmp_gt_i32_e32 vcc, v55, v52
	v_add_u32_e32 v55, 39, v72
	v_cmp_le_i32_e64 s[6:7], v37, v41
	v_cndmask_b32_e64 v31, v160, 0, vcc
	v_cmp_gt_i32_e32 vcc, v55, v52
	v_lshlrev_b32_e32 v53, 5, v37
	v_cmp_lt_i32_e64 s[8:9], v37, v41
	v_cndmask_b32_e64 v55, v160, 0, vcc
	v_lshlrev_b32_e32 v41, 5, v48
	v_lshlrev_b32_e32 v37, 6, v37
	v_or_b32_e32 v45, v45, v35
	v_lshlrev_b32_e32 v48, 6, v48
	v_or_b32_e32 v35, v49, v35
	v_readlane_b32 s10, v254, 23
	v_readlane_b32 s11, v254, 24
	v_readlane_b32 s16, v254, 29
	v_readlane_b32 s17, v254, 30
	v_readlane_b32 s18, v254, 31
	v_readlane_b32 s19, v254, 32
	v_readlane_b32 s20, v254, 33
	v_readlane_b32 s21, v254, 34
	v_readlane_b32 s22, v254, 35
	v_readlane_b32 s23, v254, 36
	v_add_u32_e32 v40, s80, v34
	v_add_u32_e32 v43, s0, v34
	v_add_u32_e32 v36, 0, v36
	v_add_u32_e32 v96, 0, v34
	v_mul_u32_u24_e32 v47, 48, v46
	v_mul_u32_u24_e32 v51, 48, v50
	v_pack_b32_f16 v31, v31, v55
	v_pack_b32_f16 v30, v30, v56
	v_pack_b32_f16 v29, v29, v54
	v_mul_u32_u24_e32 v44, 0x90, v44
	v_mul_u32_u24_e32 v103, 0x90, v91
	v_add_u32_e32 v104, v38, v37
	v_mul_u32_u24_e32 v54, 0x90, v45
	v_or_b32_e32 v55, 2, v45
	v_or_b32_e32 v56, 3, v45
	v_add_u32_e32 v105, v38, v48
	v_mul_u32_u24_e32 v38, 0x90, v35
	v_or_b32_e32 v49, 2, v35
	v_or_b32_e32 v57, 3, v35
	v_sub_u32_e32 v115, 0xbf, v32
	v_add_u32_e32 v116, 64, v32
	v_mov_b32_e32 v32, 0
	v_lshl_add_u32 v95, v72, 1, 0
	v_add_u32_e32 v102, 16, v101
	v_mul_u32_u24_e32 v106, 0x90, v46
	v_add_u32_e32 v107, v42, v37
	v_mul_u32_u24_e32 v108, 0x90, v50
	v_add_u32_e32 v109, v42, v48
	v_cmp_gt_i32_e64 s[10:11], v45, v52
	v_cmp_lt_i32_e64 s[12:13], v45, v52
	v_cmp_gt_i32_e64 s[14:15], v55, v52
	v_cmp_gt_i32_e64 s[16:17], v56, v52
	v_cmp_gt_i32_e64 s[18:19], v35, v52
	v_cmp_lt_i32_e64 s[20:21], v35, v52
	v_cmp_gt_i32_e64 s[22:23], v49, v52
	v_cmp_gt_i32_e64 s[24:25], v57, v52
	v_add_u32_e32 v110, v43, v37
	v_add_u32_e32 v111, v43, v48
	s_mov_b32 s26, 0
	v_sub_u32_e32 v112, 0, v91
	v_add_u32_e32 v113, 64, v33
	v_sub_u32_e32 v114, 0xbf, v33
	v_add_u32_e32 v117, v40, v47
	v_add_u32_e32 v118, v39, v54
	v_add_u32_e32 v119, v40, v51
	v_add_u32_e32 v120, v39, v38
	v_lshlrev_b32_e32 v84, 1, v2
	v_add_u32_e32 v121, v78, v44
	v_add_u32_e32 v122, v100, v53
	v_add_u32_e32 v123, v100, v41
	v_add_u32_e32 v124, v36, v34
	v_add_u32_e32 v125, v96, v103
	s_mov_b32 s27, 0
	s_mov_b32 s28, 0
	v_mov_b32_e32 v33, v32
	v_mov_b32_e32 v34, v32
	v_mov_b32_e32 v35, v32
	v_mov_b32_e32 v44, v32
	v_mov_b32_e32 v45, v32
	v_mov_b32_e32 v46, v32
	v_mov_b32_e32 v47, v32
	v_mov_b32_e32 v40, v32
	v_mov_b32_e32 v41, v32
	v_mov_b32_e32 v42, v32
	v_mov_b32_e32 v43, v32
	v_mov_b32_e32 v36, v32
	v_mov_b32_e32 v37, v32
	v_mov_b32_e32 v38, v32
	v_mov_b32_e32 v39, v32
	s_waitcnt vmcnt(0)
	s_branch .LBB0_901

.LBB0_901:
	v_cvt_pk_f16_f32 v49, v46, v47
	v_cvt_pk_f16_f32 v48, v44, v45
	v_cvt_pk_f16_f32 v51, v34, v35
	v_cvt_pk_f16_f32 v50, v32, v33
	s_waitcnt lgkmcnt(0)
	s_barrier
	s_waitcnt vmcnt(8)
	ds_write_b128 v92, v[4:7]
	s_waitcnt vmcnt(7)
	ds_write_b128 v92, v[8:11] offset:9216
	s_waitcnt vmcnt(6)
	ds_write_b16 v98, v12 offset:55296
	s_waitcnt vmcnt(5)
	ds_write_b16 v99, v16 offset:56448
	ds_write_b16_d16_hi v98, v12 offset:55440
	ds_write_b16_d16_hi v99, v16 offset:56592
	ds_write_b16 v98, v13 offset:55584
	ds_write_b16 v99, v17 offset:56736
	ds_write_b16_d16_hi v98, v13 offset:55728
	ds_write_b16_d16_hi v99, v17 offset:56880
	ds_write_b16 v98, v14 offset:55872
	ds_write_b16 v99, v18 offset:57024
	ds_write_b16_d16_hi v98, v14 offset:56016
	ds_write_b16_d16_hi v99, v18 offset:57168
	ds_write_b16 v98, v15 offset:56160
	ds_write_b16 v99, v19 offset:57312
	ds_write_b16_d16_hi v98, v15 offset:56304
	ds_write_b16_d16_hi v99, v19 offset:57456
	ds_write2_b64 v79, v[48:49], v[50:51] offset1:4
	v_cvt_pk_f16_f32 v49, v42, v43
	v_cvt_pk_f16_f32 v48, v40, v41
	v_cvt_pk_f16_f32 v51, v38, v39
	v_cvt_pk_f16_f32 v50, v36, v37
	v_mov_b32_e32 v52, 0
	v_mov_b32_e32 v53, 0
	v_mov_b32_e32 v54, 0
	v_mov_b32_e32 v55, 0
	ds_write2_b64 v79, v[48:49], v[50:51] offset0:8 offset1:12
	s_and_saveexec_b64 s[0:1], s[4:5]
	ds_read_b128 v[52:55], v117
	s_or_b64 exec, exec, s[0:1]
	s_waitcnt vmcnt(4)
	v_cndmask_b32_e64 v51, 0, v23, s[4:5]
	v_cndmask_b32_e64 v50, 0, v22, s[4:5]
	v_cndmask_b32_e64 v49, 0, v21, s[4:5]
	v_cndmask_b32_e64 v48, 0, v20, s[4:5]
	ds_read_b128 v[56:59], v104
	s_waitcnt lgkmcnt(1)
	v_mfma_f32_16x16x32_f16 v[52:55], v[52:55], v[48:51], 0
	s_waitcnt lgkmcnt(0)
	s_nop 6
	v_add_f32_e32 v2, v52, v56
	v_min_f32_e32 v52, 0, v2
	v_mul_f32_e64 v2, |v2|, s82
	v_exp_f32_e32 v2, v2
	s_nop 0
	v_add_f32_e32 v2, 1.0, v2
	v_cmp_gt_f32_e32 vcc, s87, v2
	s_nop 1
	v_cndmask_b32_e64 v56, 0, 32, vcc
	v_ldexp_f32 v2, v2, v56
	v_log_f32_e32 v2, v2
	s_nop 0
	v_mul_f32_e32 v56, 0x3f317217, v2
	v_fma_f32 v56, v2, s90, -v56
	v_fmac_f32_e32 v56, 0x3377d1cf, v2
	v_fmac_f32_e32 v56, 0x3f317217, v2
	v_cmp_lt_f32_e64 s[0:1], |v2|, s91
	s_nop 1
	v_cndmask_b32_e64 v2, v2, v56, s[0:1]
	v_cndmask_b32_e32 v56, 0, v161, vcc
	v_sub_f32_e32 v2, v2, v56
	v_sub_f32_e32 v2, v52, v2
	v_mul_f32_e32 v2, 0x3d800000, v2
	v_max_f32_e32 v2, -1.0, v2
	v_cvt_f16_f32_e32 v2, v2
	ds_write_b16 v118, v2
	v_add_f32_e32 v2, v53, v57
	v_min_f32_e32 v52, 0, v2
	v_mul_f32_e64 v2, |v2|, s82
	v_exp_f32_e32 v2, v2
	s_nop 0
	v_add_f32_e32 v2, 1.0, v2
	v_cmp_gt_f32_e32 vcc, s87, v2
	s_nop 1
	v_cndmask_b32_e64 v53, 0, 32, vcc
	v_ldexp_f32 v2, v2, v53
	v_log_f32_e32 v2, v2
	s_nop 0
	v_mul_f32_e32 v53, 0x3f317217, v2
	v_fma_f32 v53, v2, s90, -v53
	v_fmac_f32_e32 v53, 0x3377d1cf, v2
	v_fmac_f32_e32 v53, 0x3f317217, v2
	v_cmp_lt_f32_e64 s[0:1], |v2|, s91
	s_nop 1
	v_cndmask_b32_e64 v2, v2, v53, s[0:1]
	v_cndmask_b32_e32 v53, 0, v161, vcc
	v_sub_f32_e32 v2, v2, v53
	v_sub_f32_e32 v2, v52, v2
	v_mul_f32_e32 v2, 0x3d800000, v2
	v_max_f32_e32 v2, -1.0, v2
	v_cvt_f16_f32_e32 v2, v2
	ds_write_b16 v118, v2 offset:144
	v_add_f32_e32 v2, v54, v58
	v_min_f32_e32 v52, 0, v2
	v_mul_f32_e64 v2, |v2|, s82
	v_exp_f32_e32 v2, v2
	v_mov_b32_e32 v54, 0
	v_add_f32_e32 v2, 1.0, v2
	v_cmp_gt_f32_e32 vcc, s87, v2
	s_nop 1
	v_cndmask_b32_e64 v53, 0, 32, vcc
	v_ldexp_f32 v2, v2, v53
	v_log_f32_e32 v2, v2
	s_nop 0
	v_mul_f32_e32 v53, 0x3f317217, v2
	v_fma_f32 v53, v2, s90, -v53
	v_fmac_f32_e32 v53, 0x3377d1cf, v2
	v_fmac_f32_e32 v53, 0x3f317217, v2
	v_cmp_lt_f32_e64 s[0:1], |v2|, s91
	s_nop 1
	v_cndmask_b32_e64 v2, v2, v53, s[0:1]
	v_cndmask_b32_e32 v53, 0, v161, vcc
	v_sub_f32_e32 v2, v2, v53
	v_sub_f32_e32 v2, v52, v2
	v_mul_f32_e32 v2, 0x3d800000, v2
	v_max_f32_e32 v2, -1.0, v2
	v_cvt_f16_f32_e32 v2, v2
	ds_write_b16 v118, v2 offset:288
	v_add_f32_e32 v2, v55, v59
	v_min_f32_e32 v52, 0, v2
	v_mul_f32_e64 v2, |v2|, s82
	v_exp_f32_e32 v2, v2
	v_mov_b32_e32 v55, 0
	v_add_f32_e32 v2, 1.0, v2
	v_cmp_gt_f32_e32 vcc, s87, v2
	s_nop 1
	v_cndmask_b32_e64 v53, 0, 32, vcc
	v_ldexp_f32 v2, v2, v53
	v_log_f32_e32 v2, v2
	s_nop 0
	v_mul_f32_e32 v53, 0x3f317217, v2
	v_fma_f32 v53, v2, s90, -v53
	v_fmac_f32_e32 v53, 0x3377d1cf, v2
	v_fmac_f32_e32 v53, 0x3f317217, v2
	v_cmp_lt_f32_e64 s[0:1], |v2|, s91
	s_nop 1
	v_cndmask_b32_e64 v2, v2, v53, s[0:1]
	v_cndmask_b32_e32 v53, 0, v161, vcc
	v_sub_f32_e32 v2, v2, v53
	v_sub_f32_e32 v2, v52, v2
	v_mul_f32_e32 v2, 0x3d800000, v2
	v_max_f32_e32 v2, -1.0, v2
	v_cvt_f16_f32_e32 v2, v2
	v_mov_b32_e32 v52, 0
	v_mov_b32_e32 v53, 0
	ds_write_b16 v118, v2 offset:432
	s_and_saveexec_b64 s[0:1], s[4:5]
	ds_read_b128 v[52:55], v119
	s_or_b64 exec, exec, s[0:1]
	s_waitcnt lgkmcnt(0)
	v_mfma_f32_16x16x32_f16 v[48:51], v[52:55], v[48:51], 0
	ds_read_b128 v[52:55], v105
	s_cmp_gt_u32 s28, 2
	s_waitcnt lgkmcnt(0)
	s_nop 4
	v_add_f32_e32 v2, v48, v52
	v_min_f32_e32 v48, 0, v2
	v_mul_f32_e64 v2, |v2|, s82
	v_exp_f32_e32 v2, v2
	s_nop 0
	v_add_f32_e32 v2, 1.0, v2
	v_cmp_gt_f32_e32 vcc, s87, v2
	s_nop 1
	v_cndmask_b32_e64 v52, 0, 32, vcc
	v_ldexp_f32 v2, v2, v52
	v_log_f32_e32 v2, v2
	s_nop 0
	v_mul_f32_e32 v52, 0x3f317217, v2
	v_fma_f32 v52, v2, s90, -v52
	v_fmac_f32_e32 v52, 0x3377d1cf, v2
	v_fmac_f32_e32 v52, 0x3f317217, v2
	v_cmp_lt_f32_e64 s[0:1], |v2|, s91
	s_nop 1
	v_cndmask_b32_e64 v2, v2, v52, s[0:1]
	v_cndmask_b32_e32 v52, 0, v161, vcc
	v_sub_f32_e32 v2, v2, v52
	v_sub_f32_e32 v2, v48, v2
	v_mul_f32_e32 v2, 0x3d800000, v2
	v_max_f32_e32 v2, -1.0, v2
	v_cvt_f16_f32_e32 v2, v2
	ds_write_b16 v120, v2
	v_add_f32_e32 v2, v49, v53
	v_min_f32_e32 v48, 0, v2
	v_mul_f32_e64 v2, |v2|, s82
	v_exp_f32_e32 v2, v2
	s_nop 0
	v_add_f32_e32 v2, 1.0, v2
	v_cmp_gt_f32_e32 vcc, s87, v2
	s_nop 1
	v_cndmask_b32_e64 v49, 0, 32, vcc
	v_ldexp_f32 v2, v2, v49
	v_log_f32_e32 v2, v2
	s_nop 0
	v_mul_f32_e32 v49, 0x3f317217, v2
	v_fma_f32 v49, v2, s90, -v49
	v_fmac_f32_e32 v49, 0x3377d1cf, v2
	v_fmac_f32_e32 v49, 0x3f317217, v2
	v_cmp_lt_f32_e64 s[0:1], |v2|, s91
	s_nop 1
	v_cndmask_b32_e64 v2, v2, v49, s[0:1]
	v_cndmask_b32_e32 v49, 0, v161, vcc
	v_sub_f32_e32 v2, v2, v49
	v_sub_f32_e32 v2, v48, v2
	v_mul_f32_e32 v2, 0x3d800000, v2
	v_max_f32_e32 v2, -1.0, v2
	v_cvt_f16_f32_e32 v2, v2
	ds_write_b16 v120, v2 offset:144
	v_add_f32_e32 v2, v50, v54
	v_min_f32_e32 v48, 0, v2
	v_mul_f32_e64 v2, |v2|, s82
	v_exp_f32_e32 v2, v2
	s_nop 0
	v_add_f32_e32 v2, 1.0, v2
	v_cmp_gt_f32_e32 vcc, s87, v2
	s_nop 1
	v_cndmask_b32_e64 v49, 0, 32, vcc
	v_ldexp_f32 v2, v2, v49
	v_log_f32_e32 v2, v2
	s_nop 0
	v_mul_f32_e32 v49, 0x3f317217, v2
	v_fma_f32 v49, v2, s90, -v49
	v_fmac_f32_e32 v49, 0x3377d1cf, v2
	v_fmac_f32_e32 v49, 0x3f317217, v2
	v_cmp_lt_f32_e64 s[0:1], |v2|, s91
	s_nop 1
	v_cndmask_b32_e64 v2, v2, v49, s[0:1]
	v_cndmask_b32_e32 v49, 0, v161, vcc
	v_sub_f32_e32 v2, v2, v49
	v_sub_f32_e32 v2, v48, v2
	v_mul_f32_e32 v2, 0x3d800000, v2
	v_max_f32_e32 v2, -1.0, v2
	v_cvt_f16_f32_e32 v2, v2
	ds_write_b16 v120, v2 offset:288
	v_add_f32_e32 v2, v51, v55
	v_min_f32_e32 v48, 0, v2
	v_mul_f32_e64 v2, |v2|, s82
	v_exp_f32_e32 v2, v2
	s_nop 0
	v_add_f32_e32 v2, 1.0, v2
	v_cmp_gt_f32_e32 vcc, s87, v2
	s_nop 1
	v_cndmask_b32_e64 v49, 0, 32, vcc
	v_ldexp_f32 v2, v2, v49
	v_log_f32_e32 v2, v2
	s_nop 0
	v_mul_f32_e32 v49, 0x3f317217, v2
	v_fma_f32 v49, v2, s90, -v49
	v_fmac_f32_e32 v49, 0x3377d1cf, v2
	v_fmac_f32_e32 v49, 0x3f317217, v2
	v_cmp_lt_f32_e64 s[0:1], |v2|, s91
	s_nop 1
	v_cndmask_b32_e64 v2, v2, v49, s[0:1]
	v_cndmask_b32_e32 v49, 0, v161, vcc
	v_sub_f32_e32 v2, v2, v49
	v_sub_f32_e32 v2, v48, v2
	v_mul_f32_e32 v2, 0x3d800000, v2
	v_max_f32_e32 v2, -1.0, v2
	v_cvt_f16_f32_e32 v2, v2
	ds_write_b16 v120, v2 offset:432
	s_waitcnt lgkmcnt(0)
	s_barrier
	s_cbranch_scc1 .LBB0_909
	v_add_u32_e32 v2, s26, v116
	v_add_u32_e32 v4, s27, v115
	v_readlane_b32 s52, v254, 21
	v_cndmask_b32_e64 v2, v4, v2, s[2:3]
	v_readlane_b32 s54, v254, 23
	v_readlane_b32 s55, v254, 24
	v_add_u32_e32 v2, v2, v89
	v_mov_b32_e32 v81, v3
	v_mov_b64_e32 v[4:5], s[54:55]
	v_mad_i64_i32 v[12:13], s[0:1], v2, s71, v[4:5]
	v_lshl_add_u64 v[4:5], v[0:1], 1, v[12:13]
	v_lshlrev_b32_e32 v2, 1, v73
	v_lshl_add_u64 v[12:13], v[12:13], 0, v[80:81]
	v_mov_b32_e32 v85, v3
	v_lshl_add_u64 v[8:9], v[4:5], 0, v[2:3]
	v_lshl_add_u64 v[16:17], v[12:13], 0, v[84:85]
	global_load_dwordx4 v[4:7], v[8:9], off
	s_nop 0
	global_load_dwordx4 v[8:11], v[8:9], off offset:768
	s_nop 0
	global_load_dwordx4 v[12:15], v[16:17], off offset:1536
	s_nop 0
	global_load_dwordx4 v[16:19], v[16:17], off offset:1552
	v_readlane_b32 s53, v254, 22
	v_readlane_b32 s56, v254, 25
	v_readlane_b32 s57, v254, 26
	v_readlane_b32 s58, v254, 27
	v_readlane_b32 s59, v254, 28
	v_readlane_b32 s60, v254, 29
	v_readlane_b32 s61, v254, 30
	v_readlane_b32 s62, v254, 31
	v_readlane_b32 s63, v254, 32
	v_readlane_b32 s64, v254, 33
	v_readlane_b32 s65, v254, 34
	v_readlane_b32 s66, v254, 35
	v_readlane_b32 s67, v254, 36
	s_and_saveexec_b64 s[0:1], s[4:5]
	s_cbranch_execz .LBB0_908
	v_add_u32_e32 v2, s26, v113
	v_add_u32_e32 v20, s27, v114
	v_readlane_b32 s52, v254, 21
	v_cndmask_b32_e64 v2, v20, v2, s[2:3]
	v_readlane_b32 s54, v254, 23
	v_readlane_b32 s55, v254, 24
	v_add_u32_e32 v2, v2, v89
	v_readlane_b32 s53, v254, 22
	v_mov_b64_e32 v[20:21], s[54:55]
	v_mad_i64_i32 v[20:21], s[30:31], v2, s71, v[20:21]
	v_lshl_add_u64 v[20:21], v[74:75], 1, v[20:21]
	v_add_co_u32_e32 v20, vcc, 0x1000, v20
	v_readlane_b32 s56, v254, 25
	s_nop 0
	v_addc_co_u32_e32 v21, vcc, 0, v21, vcc
	global_load_dwordx4 v[20:23], v[20:21], off offset:512
	v_readlane_b32 s57, v254, 26
	v_readlane_b32 s58, v254, 27
	v_readlane_b32 s59, v254, 28
	v_readlane_b32 s60, v254, 29
	v_readlane_b32 s61, v254, 30
	v_readlane_b32 s62, v254, 31
	v_readlane_b32 s63, v254, 32
	v_readlane_b32 s64, v254, 33
	v_readlane_b32 s65, v254, 34
	v_readlane_b32 s66, v254, 35
	v_readlane_b32 s67, v254, 36

.LBB0_993:
	s_or_b64 exec, exec, s[0:1]
	v_readlane_b32 s8, v254, 21
	v_readlane_b32 s13, v254, 26
	v_readlane_b32 s15, v254, 28
	v_lshlrev_b32_e32 v53, 2, v46
	v_readlane_b32 s12, v254, 25
	v_readlane_b32 s14, v254, 27
	v_mov_b32_e32 v45, s15
	v_mov_b32_e32 v46, s13
	v_cndmask_b32_e64 v55, v45, v46, s[2:3]
	v_mov_b32_e32 v45, s14
	v_mov_b32_e32 v46, s12
	v_cndmask_b32_e64 v54, v45, v46, s[2:3]
	v_mul_lo_u32 v45, v82, s89
	v_add_u32_e32 v46, 0, v45
	s_movk_i32 s0, 0xff72
	v_mad_u64_u32 v[72:73], s[0:1], v82, s0, v[46:47]
	v_mul_lo_u32 v43, v43, s89
	v_readlane_b32 s0, v255, 43
	v_lshlrev_b32_e32 v1, 3, v47
	v_lshlrev_b32_e32 v41, 1, v41
	v_add3_u32 v73, s0, v43, v0
	s_add_i32 s0, 0, 0x1e400
	v_and_b32_e32 v56, 2, v41
	v_add_u32_e32 v57, s0, v52
	v_lshlrev_b32_e32 v41, 1, v51
	v_lshlrev_b32_e32 v45, 1, v80
	v_readlane_b32 s0, v255, 33
	v_ashrrev_i32_e32 v59, 7, v40
	v_readlane_b32 s6, v255, 34
	v_lshlrev_b32_e32 v74, 1, v2
	v_xor_b32_e32 v2, 16, v1
	v_readlane_b32 s9, v254, 22
	v_add3_u32 v51, s0, v41, v45
	v_lshlrev_b32_e32 v41, 4, v59
	v_lshl_add_u32 v45, v59, 12, s6
	v_lshlrev_b32_e32 v60, 8, v80
	v_mov_b32_e32 v75, v3
	v_lshl_add_u32 v88, v2, 1, v46
	v_and_b32_e32 v2, 2, v40
	v_mul_u32_u24_e32 v89, 0x480, v47
	v_add_u32_e32 v84, s0, v52
	v_add3_u32 v60, v45, v60, v52
	v_cmp_eq_u32_e32 vcc, 3, v59
	v_cmp_eq_u32_e64 s[0:1], 15, v80
	v_lshlrev_b32_e32 v45, 8, v82
	v_lshlrev_b32_e32 v62, 2, v1
	v_add_u32_e32 v63, 0, v43
	v_lshl_add_u64 v[54:55], v[54:55], 0, v[74:75]
	v_ashrrev_i32_e32 v43, 31, v42
	v_cmp_eq_u32_e64 s[8:9], 0, v2
	v_lshlrev_b32_e32 v2, 1, v89
	v_lshlrev_b32_e32 v40, 1, v82
	v_or_b32_e32 v69, v41, v80
	s_and_b64 s[68:69], vcc, s[0:1]
	v_add3_u32 v85, s6, v45, v62
	v_lshl_add_u64 v[42:43], v[42:43], 1, v[54:55]
	v_mov_b32_e32 v45, v3
	v_add3_u32 v91, 0, v2, v40
	v_or_b32_e32 v40, 2, v0
	v_cmp_gt_i32_e32 vcc, v0, v69
	v_lshl_add_u64 v[76:77], v[42:43], 0, v[44:45]
	v_mul_lo_u32 v41, v69, s89
	v_cndmask_b32_e64 v44, v160, 0, vcc
	v_cmp_lt_i32_e32 vcc, v69, v40
	v_or_b32_e32 v42, 3, v0
	v_add3_u32 v92, 0, v41, v0
	v_cndmask_b32_e64 v40, v160, 0, vcc
	v_cmp_lt_i32_e32 vcc, v0, v69
	v_or_b32_e32 v41, 4, v0
	v_lshl_add_u32 v83, v1, 1, v46
	v_cndmask_b32_e32 v45, 0, v160, vcc
	v_cmp_gt_i32_e32 vcc, v42, v69
	v_or_b32_e32 v43, 5, v0
	v_or_b32_e32 v42, 6, v0
	v_cndmask_b32_e64 v46, v160, 0, vcc
	v_cmp_gt_i32_e32 vcc, v41, v69
	v_cmp_gt_u32_e64 s[6:7], 4, v47
	v_add_u32_e32 v79, 38, v0
	v_cndmask_b32_e64 v41, v160, 0, vcc
	v_cmp_gt_i32_e32 vcc, v43, v69
	v_or_b32_e32 v43, 7, v0
	v_or_b32_e32 v65, 1, v56
	v_cndmask_b32_e64 v47, v160, 0, vcc
	v_cmp_gt_i32_e32 vcc, v42, v69
	v_readlane_b32 s10, v254, 23
	v_readlane_b32 s11, v254, 24
	v_cndmask_b32_e64 v42, v160, 0, vcc
	v_cmp_gt_i32_e32 vcc, v43, v69
	v_readlane_b32 s0, v255, 37
	v_add_u32_e32 v90, v72, v2
	v_cndmask_b32_e64 v43, v160, 0, vcc
	v_pack_b32_f16 v43, v42, v43
	v_pack_b32_f16 v42, v41, v47
	v_pack_b32_f16 v41, v40, v46
	v_pack_b32_f16 v40, v44, v45
	v_or_b32_e32 v44, 32, v0
	v_cmp_gt_i32_e32 vcc, v44, v69
	v_add_u32_e32 v45, 33, v0
	v_add_u32_e32 v46, 34, v0
	v_cndmask_b32_e64 v44, v160, 0, vcc
	v_cmp_gt_i32_e32 vcc, v45, v69
	v_add_u32_e32 v47, 36, v0
	v_lshlrev_b32_e32 v2, 4, v56
	v_cndmask_b32_e64 v75, v160, 0, vcc
	v_cmp_gt_i32_e32 vcc, v46, v69
	v_add_u32_e32 v46, 35, v0
	v_lshlrev_b32_e32 v66, 4, v65
	v_cndmask_b32_e64 v45, v160, 0, vcc
	v_cmp_gt_i32_e32 vcc, v46, v69
	v_or_b32_e32 v55, v2, v80
	v_or_b32_e32 v67, v66, v80
	v_cndmask_b32_e64 v78, v160, 0, vcc
	v_cmp_gt_i32_e32 vcc, v47, v69
	v_add_u32_e32 v47, 37, v0
	v_pack_b32_f16 v44, v44, v75
	v_cndmask_b32_e64 v46, v160, 0, vcc
	v_cmp_gt_i32_e32 vcc, v47, v69
	v_cmp_le_i32_e64 s[10:11], v56, v59
	v_lshlrev_b32_e32 v75, 5, v56
	v_cndmask_b32_e64 v93, v160, 0, vcc
	v_cmp_gt_i32_e32 vcc, v79, v69
	v_add_u32_e32 v79, 39, v0
	v_pack_b32_f16 v46, v46, v93
	v_cndmask_b32_e64 v47, v160, 0, vcc
	v_cmp_gt_i32_e32 vcc, v79, v69
	v_add_u32_e32 v93, s0, v62
	v_or_b32_e32 v62, 1, v1
	v_cndmask_b32_e64 v79, v160, 0, vcc
	v_cmp_lt_i32_e64 s[12:13], v56, v59
	v_lshlrev_b32_e32 v59, 5, v65
	v_lshlrev_b32_e32 v56, 6, v56
	v_or_b32_e32 v2, v2, v53
	v_lshlrev_b32_e32 v65, 6, v65
	v_or_b32_e32 v53, v66, v53
	v_readlane_b32 s16, v254, 29
	v_readlane_b32 s17, v254, 30
	v_readlane_b32 s18, v254, 31
	v_readlane_b32 s19, v254, 32
	v_readlane_b32 s20, v254, 33
	v_readlane_b32 s21, v254, 34
	v_readlane_b32 s22, v254, 35
	v_readlane_b32 s23, v254, 36
	v_add_u32_e32 v58, s80, v52
	v_add_u32_e32 v61, s0, v52
	v_add_u32_e32 v87, 0, v52
	v_and_b32_e32 v54, 8, v1
	v_mul_u32_u24_e32 v64, 48, v55
	v_mul_u32_u24_e32 v68, 48, v67
	v_pack_b32_f16 v47, v47, v79
	v_pack_b32_f16 v45, v45, v78
	v_mul_u32_u24_e32 v62, 0x90, v62
	v_mul_u32_u24_e32 v95, 0x90, v80
	v_add_u32_e32 v96, v57, v56
	v_mul_u32_u24_e32 v78, 0x90, v2
	v_or_b32_e32 v79, 2, v2
	v_or_b32_e32 v102, 3, v2
	v_add_u32_e32 v97, v57, v65
	v_mul_u32_u24_e32 v57, 0x90, v53
	v_or_b32_e32 v66, 2, v53
	v_or_b32_e32 v103, 3, v53
	s_mov_b32 s31, s80
	v_lshl_add_u32 v86, v0, 1, 0
	s_mov_b32 s80, 0
	v_add_u32_e32 v94, 16, v93
	v_mul_u32_u24_e32 v98, 0x90, v55
	v_add_u32_e32 v99, v60, v56
	v_mul_u32_u24_e32 v100, 0x90, v67
	v_add_u32_e32 v101, v60, v65
	v_cmp_gt_i32_e64 s[14:15], v2, v69
	v_cmp_lt_i32_e64 s[16:17], v2, v69
	v_cmp_gt_i32_e64 s[18:19], v79, v69
	v_cmp_gt_i32_e64 s[20:21], v102, v69
	v_cmp_gt_i32_e64 s[22:23], v53, v69
	v_cmp_lt_i32_e64 s[24:25], v53, v69
	v_cmp_gt_i32_e64 s[26:27], v66, v69
	v_cmp_gt_i32_e64 s[28:29], v103, v69
	v_add_u32_e32 v102, v61, v56
	v_add_u32_e32 v103, v61, v65
	v_sub_u32_e32 v104, 0, v80
	v_sub_u32_e32 v105, 0, v82
	v_add_u32_e32 v106, 64, v49
	v_sub_u32_e32 v107, 0x7bf, v49
	v_add_u32_e32 v108, v58, v64
	v_add_u32_e32 v109, v51, v78
	v_add_u32_e32 v110, v58, v68
	v_add_u32_e32 v111, v51, v57
	v_lshlrev_b32_e32 v2, 1, v48
	v_lshlrev_b32_e32 v78, 1, v50
	v_lshlrev_b32_e32 v112, 2, v54
	v_add_u32_e32 v113, v72, v62
	v_add_u32_e32 v114, v92, v75
	v_add_u32_e32 v115, v92, v59
	v_add_u32_e32 v116, v63, v52
	v_add_u32_e32 v117, v87, v95
	s_mov_b32 s96, 0
	s_mov_b32 s30, 0
	s_waitcnt vmcnt(0)
	s_branch .LBB0_995

.LBB0_995:
	s_waitcnt vmcnt(16)
	v_cvt_pk_f16_f32 v49, v10, v11
	v_cvt_pk_f16_f32 v48, v8, v9
	s_waitcnt vmcnt(12)
	v_cvt_pk_f16_f32 v51, v6, v7
	v_cvt_pk_f16_f32 v50, v4, v5
	s_waitcnt lgkmcnt(0)
	s_barrier
	s_waitcnt vmcnt(8)
	ds_write_b128 v83, v[20:23]
	s_waitcnt vmcnt(7)
	ds_write_b128 v83, v[24:27] offset:9216
	s_waitcnt vmcnt(6)
	ds_write_b16 v90, v28 offset:55296
	s_waitcnt vmcnt(5)
	ds_write_b16 v91, v32 offset:56448
	ds_write_b16_d16_hi v90, v28 offset:55440
	ds_write_b16_d16_hi v91, v32 offset:56592
	ds_write_b16 v90, v29 offset:55584
	ds_write_b16 v91, v33 offset:56736
	ds_write_b16_d16_hi v90, v29 offset:55728
	ds_write_b16_d16_hi v91, v33 offset:56880
	ds_write_b16 v90, v30 offset:55872
	ds_write_b16 v91, v34 offset:57024
	ds_write_b16_d16_hi v90, v30 offset:56016
	ds_write_b16_d16_hi v91, v34 offset:57168
	ds_write_b16 v90, v31 offset:56160
	ds_write_b16 v91, v35 offset:57312
	ds_write_b16_d16_hi v90, v31 offset:56304
	ds_write_b16_d16_hi v91, v35 offset:57456
	ds_write2_b64 v73, v[48:49], v[50:51] offset1:4
	v_cvt_pk_f16_f32 v49, v18, v19
	v_cvt_pk_f16_f32 v48, v16, v17
	v_cvt_pk_f16_f32 v51, v14, v15
	v_cvt_pk_f16_f32 v50, v12, v13
	ds_write2_b64 v73, v[48:49], v[50:51] offset0:8 offset1:12
	v_mov_b32_e32 v48, 0
	v_mov_b32_e32 v56, 0
	v_mov_b32_e32 v57, 0
	v_mov_b32_e32 v58, 0
	v_mov_b32_e32 v59, 0
	s_and_saveexec_b64 s[0:1], s[4:5]
	ds_read_b128 v[56:59], v108
	s_or_b64 exec, exec, s[0:1]
	s_waitcnt vmcnt(4)
	v_cndmask_b32_e64 v55, 0, v39, s[4:5]
	v_cndmask_b32_e64 v54, 0, v38, s[4:5]
	v_cndmask_b32_e64 v53, 0, v37, s[4:5]
	v_cndmask_b32_e64 v52, 0, v36, s[4:5]
	ds_read_b128 v[60:63], v96
	s_waitcnt lgkmcnt(1)
	v_mfma_f32_16x16x32_f16 v[56:59], v[56:59], v[52:55], 0
	s_waitcnt lgkmcnt(0)
	s_nop 6
	v_add_f32_e32 v49, v56, v60
	v_min_f32_e32 v50, 0, v49
	v_mul_f32_e64 v49, |v49|, s82
	v_exp_f32_e32 v49, v49
	s_nop 0
	v_add_f32_e32 v49, 1.0, v49
	v_cmp_gt_f32_e32 vcc, s87, v49
	s_nop 1
	v_cndmask_b32_e64 v51, 0, 32, vcc
	v_ldexp_f32 v49, v49, v51
	v_log_f32_e32 v49, v49
	s_nop 0
	v_mul_f32_e32 v51, 0x3f317217, v49
	v_fma_f32 v51, v49, s90, -v51
	v_fmac_f32_e32 v51, 0x3377d1cf, v49
	v_fmac_f32_e32 v51, 0x3f317217, v49
	v_cmp_lt_f32_e64 s[0:1], |v49|, s91
	s_nop 1
	v_cndmask_b32_e64 v49, v49, v51, s[0:1]
	v_cndmask_b32_e32 v51, 0, v161, vcc
	v_sub_f32_e32 v49, v49, v51
	v_sub_f32_e32 v49, v50, v49
	v_mul_f32_e32 v49, 0x3d800000, v49
	v_max_f32_e32 v49, -1.0, v49
	v_cvt_f16_f32_e32 v49, v49
	ds_write_b16 v109, v49
	v_add_f32_e32 v49, v57, v61
	v_min_f32_e32 v50, 0, v49
	v_mul_f32_e64 v49, |v49|, s82
	v_exp_f32_e32 v49, v49
	s_nop 0
	v_add_f32_e32 v49, 1.0, v49
	v_cmp_gt_f32_e32 vcc, s87, v49
	s_nop 1
	v_cndmask_b32_e64 v51, 0, 32, vcc
	v_ldexp_f32 v49, v49, v51
	v_log_f32_e32 v49, v49
	s_nop 0
	v_mul_f32_e32 v51, 0x3f317217, v49
	v_fma_f32 v51, v49, s90, -v51
	v_fmac_f32_e32 v51, 0x3377d1cf, v49
	v_fmac_f32_e32 v51, 0x3f317217, v49
	v_cmp_lt_f32_e64 s[0:1], |v49|, s91
	s_nop 1
	v_cndmask_b32_e64 v49, v49, v51, s[0:1]
	v_cndmask_b32_e32 v51, 0, v161, vcc
	v_sub_f32_e32 v49, v49, v51
	v_sub_f32_e32 v49, v50, v49
	v_mul_f32_e32 v49, 0x3d800000, v49
	v_max_f32_e32 v49, -1.0, v49
	v_cvt_f16_f32_e32 v49, v49
	ds_write_b16 v109, v49 offset:144
	v_add_f32_e32 v49, v58, v62
	v_min_f32_e32 v50, 0, v49
	v_mul_f32_e64 v49, |v49|, s82
	v_exp_f32_e32 v49, v49
	s_nop 0
	v_add_f32_e32 v49, 1.0, v49
	v_cmp_gt_f32_e32 vcc, s87, v49
	s_nop 1
	v_cndmask_b32_e64 v51, 0, 32, vcc
	v_ldexp_f32 v49, v49, v51
	v_log_f32_e32 v49, v49
	s_nop 0
	v_mul_f32_e32 v51, 0x3f317217, v49
	v_fma_f32 v51, v49, s90, -v51
	v_fmac_f32_e32 v51, 0x3377d1cf, v49
	v_fmac_f32_e32 v51, 0x3f317217, v49
	v_cmp_lt_f32_e64 s[0:1], |v49|, s91
	s_nop 1
	v_cndmask_b32_e64 v49, v49, v51, s[0:1]
	v_cndmask_b32_e32 v51, 0, v161, vcc
	v_sub_f32_e32 v49, v49, v51
	v_sub_f32_e32 v49, v50, v49
	v_mul_f32_e32 v49, 0x3d800000, v49
	v_max_f32_e32 v49, -1.0, v49
	v_cvt_f16_f32_e32 v49, v49
	ds_write_b16 v109, v49 offset:288
	v_add_f32_e32 v49, v59, v63
	v_min_f32_e32 v50, 0, v49
	v_mul_f32_e64 v49, |v49|, s82
	v_exp_f32_e32 v49, v49
	s_nop 0
	v_add_f32_e32 v49, 1.0, v49
	v_cmp_gt_f32_e32 vcc, s87, v49
	s_nop 1
	v_cndmask_b32_e64 v51, 0, 32, vcc
	v_ldexp_f32 v49, v49, v51
	v_log_f32_e32 v49, v49
	s_nop 0
	v_mul_f32_e32 v51, 0x3f317217, v49
	v_fma_f32 v51, v49, s90, -v51
	v_fmac_f32_e32 v51, 0x3377d1cf, v49
	v_fmac_f32_e32 v51, 0x3f317217, v49
	v_cmp_lt_f32_e64 s[0:1], |v49|, s91
	s_nop 1
	v_cndmask_b32_e64 v49, v49, v51, s[0:1]
	v_cndmask_b32_e32 v51, 0, v161, vcc
	v_sub_f32_e32 v49, v49, v51
	v_sub_f32_e32 v49, v50, v49
	v_mul_f32_e32 v49, 0x3d800000, v49
	v_max_f32_e32 v49, -1.0, v49
	v_cvt_f16_f32_e32 v49, v49
	v_mov_b32_e32 v50, 0
	v_mov_b32_e32 v51, 0
	ds_write_b16 v109, v49 offset:432
	v_mov_b32_e32 v49, 0
	s_and_saveexec_b64 s[0:1], s[4:5]
	ds_read_b128 v[48:51], v110
	s_or_b64 exec, exec, s[0:1]
	s_waitcnt lgkmcnt(0)
	v_mfma_f32_16x16x32_f16 v[48:51], v[48:51], v[52:55], 0
	ds_read_b128 v[52:55], v97
	s_cmp_gt_u32 s30, 30
	s_waitcnt lgkmcnt(0)
	s_nop 4
	v_add_f32_e32 v48, v48, v52
	v_min_f32_e32 v52, 0, v48
	v_mul_f32_e64 v48, |v48|, s82
	v_exp_f32_e32 v48, v48
	s_nop 0
	v_add_f32_e32 v48, 1.0, v48
	v_cmp_gt_f32_e32 vcc, s87, v48
	s_nop 1
	v_cndmask_b32_e64 v56, 0, 32, vcc
	v_ldexp_f32 v48, v48, v56
	v_log_f32_e32 v48, v48
	s_nop 0
	v_mul_f32_e32 v56, 0x3f317217, v48
	v_fma_f32 v56, v48, s90, -v56
	v_fmac_f32_e32 v56, 0x3377d1cf, v48
	v_fmac_f32_e32 v56, 0x3f317217, v48
	v_cmp_lt_f32_e64 s[0:1], |v48|, s91
	s_nop 1
	v_cndmask_b32_e64 v48, v48, v56, s[0:1]
	v_cndmask_b32_e32 v56, 0, v161, vcc
	v_sub_f32_e32 v48, v48, v56
	v_sub_f32_e32 v48, v52, v48
	v_mul_f32_e32 v48, 0x3d800000, v48
	v_max_f32_e32 v48, -1.0, v48
	v_cvt_f16_f32_e32 v48, v48
	v_add_u32_e32 v56, s96, v105
	ds_write_b16 v111, v48
	v_add_f32_e32 v48, v49, v53
	v_min_f32_e32 v49, 0, v48
	v_mul_f32_e64 v48, |v48|, s82
	v_exp_f32_e32 v48, v48
	s_nop 0
	v_add_f32_e32 v48, 1.0, v48
	v_cmp_gt_f32_e32 vcc, s87, v48
	s_nop 1
	v_cndmask_b32_e64 v52, 0, 32, vcc
	v_ldexp_f32 v48, v48, v52
	v_log_f32_e32 v48, v48
	s_nop 0
	v_mul_f32_e32 v52, 0x3f317217, v48
	v_fma_f32 v52, v48, s90, -v52
	v_fmac_f32_e32 v52, 0x3377d1cf, v48
	v_fmac_f32_e32 v52, 0x3f317217, v48
	v_cmp_lt_f32_e64 s[0:1], |v48|, s91
	s_nop 1
	v_cndmask_b32_e64 v48, v48, v52, s[0:1]
	v_cndmask_b32_e32 v52, 0, v161, vcc
	v_sub_f32_e32 v48, v48, v52
	v_sub_f32_e32 v48, v49, v48
	v_mul_f32_e32 v48, 0x3d800000, v48
	v_max_f32_e32 v48, -1.0, v48
	v_cvt_f16_f32_e32 v48, v48
	ds_write_b16 v111, v48 offset:144
	v_add_f32_e32 v48, v50, v54
	v_min_f32_e32 v49, 0, v48
	v_mul_f32_e64 v48, |v48|, s82
	v_exp_f32_e32 v48, v48
	s_nop 0
	v_add_f32_e32 v48, 1.0, v48
	v_cmp_gt_f32_e32 vcc, s87, v48
	s_nop 1
	v_cndmask_b32_e64 v50, 0, 32, vcc
	v_ldexp_f32 v48, v48, v50
	v_log_f32_e32 v48, v48
	s_nop 0
	v_mul_f32_e32 v50, 0x3f317217, v48
	v_fma_f32 v50, v48, s90, -v50
	v_fmac_f32_e32 v50, 0x3377d1cf, v48
	v_fmac_f32_e32 v50, 0x3f317217, v48
	v_cmp_lt_f32_e64 s[0:1], |v48|, s91
	s_nop 1
	v_cndmask_b32_e64 v48, v48, v50, s[0:1]
	v_cndmask_b32_e32 v50, 0, v161, vcc
	v_sub_f32_e32 v48, v48, v50
	v_sub_f32_e32 v48, v49, v48
	v_mul_f32_e32 v48, 0x3d800000, v48
	v_max_f32_e32 v48, -1.0, v48
	v_cvt_f16_f32_e32 v48, v48
	ds_write_b16 v111, v48 offset:288
	v_add_f32_e32 v48, v51, v55
	v_min_f32_e32 v49, 0, v48
	v_mul_f32_e64 v48, |v48|, s82
	v_exp_f32_e32 v48, v48
	s_nop 0
	v_add_f32_e32 v48, 1.0, v48
	v_cmp_gt_f32_e32 vcc, s87, v48
	s_nop 1
	v_cndmask_b32_e64 v50, 0, 32, vcc
	v_ldexp_f32 v48, v48, v50
	v_log_f32_e32 v48, v48
	s_nop 0
	v_mul_f32_e32 v50, 0x3f317217, v48
	v_fma_f32 v50, v48, s90, -v50
	v_fmac_f32_e32 v50, 0x3377d1cf, v48
	v_fmac_f32_e32 v50, 0x3f317217, v48
	v_cmp_lt_f32_e64 s[0:1], |v48|, s91
	s_nop 1
	v_cndmask_b32_e64 v48, v48, v50, s[0:1]
	v_cndmask_b32_e32 v50, 0, v161, vcc
	v_sub_f32_e32 v48, v48, v50
	v_sub_f32_e32 v48, v49, v48
	v_mul_f32_e32 v48, 0x3d800000, v48
	v_max_f32_e32 v48, -1.0, v48
	v_cvt_f16_f32_e32 v48, v48
	ds_write_b16 v111, v48 offset:432
	s_waitcnt lgkmcnt(0)
	s_barrier
	s_cbranch_scc1 .LBB0_1003
	v_add3_u32 v20, v82, s80, 64
	v_add_u32_e32 v21, 0x7bf, v56
	v_readlane_b32 s52, v254, 21
	v_cndmask_b32_e64 v20, v21, v20, s[2:3]
	v_readlane_b32 s54, v254, 23
	v_readlane_b32 s55, v254, 24
	v_add_u32_e32 v22, v20, v81
	v_mov_b32_e32 v75, v3
	v_mov_b64_e32 v[20:21], s[54:55]
	v_mad_i64_i32 v[28:29], s[0:1], v22, s71, v[20:21]
	v_lshl_add_u64 v[20:21], v[28:29], 0, v[2:3]
	v_lshlrev_b32_e32 v22, 1, v1
	v_mov_b32_e32 v23, v3
	v_lshl_add_u64 v[28:29], v[28:29], 0, v[74:75]
	v_mov_b32_e32 v79, v3
	v_lshl_add_u64 v[24:25], v[20:21], 0, v[22:23]
	v_lshl_add_u64 v[32:33], v[28:29], 0, v[78:79]
	global_load_dwordx4 v[20:23], v[24:25], off
	s_nop 0
	global_load_dwordx4 v[24:27], v[24:25], off offset:768
	s_nop 0
	global_load_dwordx4 v[28:31], v[32:33], off offset:1536
	s_nop 0
	global_load_dwordx4 v[32:35], v[32:33], off offset:1552
	v_readlane_b32 s53, v254, 22
	v_readlane_b32 s56, v254, 25
	v_readlane_b32 s57, v254, 26
	v_readlane_b32 s58, v254, 27
	v_readlane_b32 s59, v254, 28
	v_readlane_b32 s60, v254, 29
	v_readlane_b32 s61, v254, 30
	v_readlane_b32 s62, v254, 31
	v_readlane_b32 s63, v254, 32
	v_readlane_b32 s64, v254, 33
	v_readlane_b32 s65, v254, 34
	v_readlane_b32 s66, v254, 35
	v_readlane_b32 s67, v254, 36
	s_and_saveexec_b64 s[0:1], s[4:5]
	s_cbranch_execz .LBB0_1002
	v_add_u32_e32 v36, s80, v106
	v_add_u32_e32 v37, s96, v107
	v_readlane_b32 s52, v254, 21
	v_cndmask_b32_e64 v36, v37, v36, s[2:3]
	v_readlane_b32 s54, v254, 23
	v_readlane_b32 s55, v254, 24
	v_add_u32_e32 v38, v36, v81
	v_readlane_b32 s53, v254, 22
	v_mov_b64_e32 v[36:37], s[54:55]
	v_mad_i64_i32 v[36:37], vcc, v38, s71, v[36:37]
	v_lshl_add_u64 v[36:37], v[70:71], 1, v[36:37]
	v_add_co_u32_e32 v36, vcc, 0x1000, v36
	v_readlane_b32 s56, v254, 25
	s_nop 0
	v_addc_co_u32_e32 v37, vcc, 0, v37, vcc
	global_load_dwordx4 v[36:39], v[36:37], off offset:512
	v_readlane_b32 s57, v254, 26
	v_readlane_b32 s58, v254, 27
	v_readlane_b32 s59, v254, 28
	v_readlane_b32 s60, v254, 29
	v_readlane_b32 s61, v254, 30
	v_readlane_b32 s62, v254, 31
	v_readlane_b32 s63, v254, 32
	v_readlane_b32 s64, v254, 33
	v_readlane_b32 s65, v254, 34
	v_readlane_b32 s66, v254, 35
	v_readlane_b32 s67, v254, 36
